# all six GEMM K-loops: LDS-DMA staging rebalanced 4/4 per super-phase
# speedup vs baseline: 1.0060x; 1.0060x over previous
; #define PG8_STAGE(bufoff, gbase, voff) do { _Pragma("unroll") for (int _i = 0; _i < 2; ++_i) \
;         __builtin_amdgcn_global_load_lds((const unsigned*)((const char*)(gbase) + (voff)[_i]), (PG8_LAS unsigned*)(lds + (bufoff) + ldsw + _i * 8192), 16, 0, 0); } while (0)
; #define PG8_LDA(dst, b, h) do { _Pragma("unroll") for (int m = 0; m < 4; ++m) _Pragma("unroll") for (int k = 0; k < 2; ++k) dst[m][k] = *(const PG8_LAS bf16x8*)(lds + PG8_SA(b, h) + aoff + m * 2048 + k * 1024); } while (0)
; #define PG8_LDB(dst, b, h) do { _Pragma("unroll") for (int n = 0; n < 2; ++n) _Pragma("unroll") for (int k = 0; k < 2; ++k) dst[n][k] = *(const PG8_LAS bf16x8*)(lds + PG8_SB(b, h) + boff + n * 2048 + k * 1024); } while (0)
; #define PG8_MMA(ai, bj, At, Bt) do { __builtin_amdgcn_s_setprio(1); _Pragma("unroll") for (int m = 0; m < 4; ++m) _Pragma("unroll") for (int n = 0; n < 2; ++n) _Pragma("unroll") for (int k = 0; k < 2; ++k) \
;         acc[ai][bj][m][n] = __builtin_amdgcn_mfma_f32_16x16x32_bf16(Bt[n][k], At[m][k], acc[ai][bj][m][n], 0, 0, 0); __builtin_amdgcn_s_setprio(0); } while (0)
; #define PG8_WAIT_V(n) asm volatile("s_waitcnt vmcnt(" #n ")" ::: "memory")
; #define PG8_WAIT_L(n) asm volatile("s_waitcnt lgkmcnt(" #n ")" ::: "memory")
; #define PG8_BAR __builtin_amdgcn_s_barrier()
; #define PG8_SCHED __builtin_amdgcn_sched_barrier(0)
; template <class Epi, class Sched, bool ALIGN_EPI = false, bool SP2 = false>
; __device__ __forceinline__ void gemm_phase(PG8_LAS unsigned char* lds, const Gemm g, const Sched& S, const Epi& E) {
;     ...
;             PG8_LDB(B0, 0, 0); PG8_LDB(B1, 0, 1); PG8_SCHED; PG8_LDA(At, 0, 0); PG8_STAGE(PG8_SA(1, 1), a1 + hstep, voffA);
;             PG8_WAIT_V(8); PG8_WAIT_L(0); PG8_BAR; PG8_MMA(0, 0, At, B0); PG8_MMA(0, 1, At, B1); PG8_BAR; PG8_SCHED;
;             PG8_LDA(At, 0, 1); PG8_STAGE(PG8_SB(0, 0), b2, voffB); PG8_STAGE(PG8_SB(0, 1), b2 + hstep, voffB); PG8_STAGE(PG8_SA(0, 0), a2, voffA);
;             PG8_WAIT_V(8); PG8_WAIT_L(0); PG8_BAR; PG8_MMA(1, 0, At, B0); PG8_MMA(1, 1, At, B1); PG8_BAR; PG8_SCHED;
.LBB0_180:
	s_add_u32 s36, s34, 0xfff00000
	s_addc_u32 s37, s35, -1
	v_lshl_add_u64 v[156:157], s[36:37], 0, v[138:139]
	s_mov_b32 m0, s45
	s_nop 0
	global_load_lds_dwordx4 v[156:157], off
	v_lshl_add_u64 v[156:157], s[36:37], 0, v[142:143]
	s_mov_b32 m0, s46
	s_nop 0
	global_load_lds_dwordx4 v[156:157], off
	s_add_u32 s36, s36, 0x80
	s_addc_u32 s37, s37, 0
	ds_read_b128 v[130:133], v170
	ds_read_b128 v[134:137], v170 offset:1024
	ds_read_b128 v[178:181], v170 offset:2048
	ds_read_b128 v[182:185], v170 offset:3072
	ds_read_b128 v[186:189], v171
	ds_read_b128 v[190:193], v171 offset:1024
	ds_read_b128 v[194:197], v171 offset:2048
	ds_read_b128 v[200:203], v171 offset:3072
	s_cmp_eq_u32 s56, 60
	s_cselect_b32 s39, s7, s37
	s_cselect_b32 s38, s25, s36
	s_cselect_b32 s37, s15, s55
	s_cselect_b32 s36, s31, s54
	v_lshl_add_u64 v[156:157], s[34:35], 0, v[148:149]
	s_add_i32 m0, s40, 0xc000
	ds_read_b128 v[204:207], v172
	ds_read_b128 v[208:211], v172 offset:1024
	ds_read_b128 v[212:215], v172 offset:2048
	ds_read_b128 v[216:219], v172 offset:3072
	ds_read_b128 v[220:223], v172 offset:4096
	ds_read_b128 v[224:227], v172 offset:5120
	ds_read_b128 v[228:231], v172 offset:6144
	ds_read_b128 v[232:235], v172 offset:7168
	global_load_lds_dwordx4 v[156:157], off
	v_lshl_add_u64 v[156:157], s[34:35], 0, v[150:151]
	s_add_i32 m0, s40, 0xe000
	s_nop 0
	global_load_lds_dwordx4 v[156:157], off
	s_waitcnt vmcnt(8)
	s_waitcnt lgkmcnt(0)
	s_barrier
	s_setprio 1
	s_waitcnt lgkmcnt(0)
	v_mfma_f32_16x16x32_bf16 v[126:129], v[130:133], v[204:207], v[126:129]
	v_mfma_f32_16x16x32_bf16 v[122:125], v[178:181], v[204:207], v[122:125]
	v_mfma_f32_16x16x32_bf16 v[110:113], v[130:133], v[212:215], v[110:113]
	v_mfma_f32_16x16x32_bf16 v[106:109], v[178:181], v[212:215], v[106:109]
	v_mfma_f32_16x16x32_bf16 v[94:97], v[130:133], v[220:223], v[94:97]
	v_mfma_f32_16x16x32_bf16 v[90:93], v[178:181], v[220:223], v[90:93]
	v_mfma_f32_16x16x32_bf16 v[78:81], v[130:133], v[228:231], v[78:81]
	v_mfma_f32_16x16x32_bf16 v[74:77], v[178:181], v[228:231], v[74:77]
	v_mfma_f32_16x16x32_bf16 v[126:129], v[134:137], v[208:211], v[126:129]
	v_mfma_f32_16x16x32_bf16 v[122:125], v[182:185], v[208:211], v[122:125]
	v_mfma_f32_16x16x32_bf16 v[110:113], v[134:137], v[216:219], v[110:113]
	v_mfma_f32_16x16x32_bf16 v[106:109], v[182:185], v[216:219], v[106:109]
	v_mfma_f32_16x16x32_bf16 v[94:97], v[134:137], v[224:227], v[94:97]
	v_mfma_f32_16x16x32_bf16 v[90:93], v[182:185], v[224:227], v[90:93]
	v_mfma_f32_16x16x32_bf16 v[78:81], v[134:137], v[232:235], v[78:81]
	v_mfma_f32_16x16x32_bf16 v[74:77], v[182:185], v[232:235], v[74:77]
	s_setprio 0
	s_setprio 1
	v_mfma_f32_16x16x32_bf16 v[118:121], v[186:189], v[204:207], v[118:121]
	v_mfma_f32_16x16x32_bf16 v[114:117], v[194:197], v[204:207], v[114:117]
	v_mfma_f32_16x16x32_bf16 v[102:105], v[186:189], v[212:215], v[102:105]
	v_mfma_f32_16x16x32_bf16 v[98:101], v[194:197], v[212:215], v[98:101]
	v_mfma_f32_16x16x32_bf16 v[86:89], v[186:189], v[220:223], v[86:89]
	v_mfma_f32_16x16x32_bf16 v[82:85], v[194:197], v[220:223], v[82:85]
	v_mfma_f32_16x16x32_bf16 v[70:73], v[186:189], v[228:231], v[70:73]
	v_mfma_f32_16x16x32_bf16 v[66:69], v[194:197], v[228:231], v[66:69]
	v_mfma_f32_16x16x32_bf16 v[118:121], v[190:193], v[208:211], v[118:121]
	v_mfma_f32_16x16x32_bf16 v[114:117], v[200:203], v[208:211], v[114:117]
	v_mfma_f32_16x16x32_bf16 v[102:105], v[190:193], v[216:219], v[102:105]
	v_mfma_f32_16x16x32_bf16 v[98:101], v[200:203], v[216:219], v[98:101]
	v_mfma_f32_16x16x32_bf16 v[86:89], v[190:193], v[224:227], v[86:89]
	v_mfma_f32_16x16x32_bf16 v[82:85], v[200:203], v[224:227], v[82:85]
	v_mfma_f32_16x16x32_bf16 v[70:73], v[190:193], v[232:235], v[70:73]
	v_mfma_f32_16x16x32_bf16 v[66:69], v[200:203], v[232:235], v[66:69]
	s_setprio 0
	s_barrier
	s_add_i32 s57, s49, s33
	v_lshl_add_u64 v[156:157], s[36:37], 0, v[140:141]
	s_mov_b32 m0, s57
	ds_read_b128 v[204:207], v172 offset:16384
	ds_read_b128 v[208:211], v172 offset:17408
	ds_read_b128 v[212:215], v172 offset:18432
	ds_read_b128 v[216:219], v172 offset:19456
	ds_read_b128 v[220:223], v172 offset:20480
	ds_read_b128 v[224:227], v172 offset:21504
	ds_read_b128 v[228:231], v172 offset:22528
	ds_read_b128 v[232:235], v172 offset:23552
	global_load_lds_dwordx4 v[156:157], off
	s_add_i32 m0, s57, 0x2000
	s_add_u32 s58, s36, 0x100000
	v_lshl_add_u64 v[236:237], s[36:37], 0, v[144:145]
	s_addc_u32 s59, s37, 0
	s_add_i32 s57, s50, s33
	global_load_lds_dwordx4 v[236:237], off
	v_lshl_add_u64 v[238:239], s[58:59], 0, v[140:141]
	s_mov_b32 m0, s57
	v_lshl_add_u64 v[240:241], s[38:39], 0, v[142:143]
	global_load_lds_dwordx4 v[238:239], off
	v_lshl_add_u64 v[238:239], s[58:59], 0, v[144:145]
	s_add_i32 m0, s57, 0x2000
	s_nop 0
	global_load_lds_dwordx4 v[238:239], off
	v_lshl_add_u64 v[238:239], s[38:39], 0, v[138:139]
	s_waitcnt vmcnt(6)
	s_waitcnt lgkmcnt(0)
	s_barrier
; #define PG8_STAGE(bufoff, gbase, voff) do { _Pragma("unroll") for (int _i = 0; _i < 2; ++_i) \
;         __builtin_amdgcn_global_load_lds((const unsigned*)((const char*)(gbase) + (voff)[_i]), (PG8_LAS unsigned*)(lds + (bufoff) + ldsw + _i * 8192), 16, 0, 0); } while (0)
; #define PG8_LDA(dst, b, h) do { _Pragma("unroll") for (int m = 0; m < 4; ++m) _Pragma("unroll") for (int k = 0; k < 2; ++k) dst[m][k] = *(const PG8_LAS bf16x8*)(lds + PG8_SA(b, h) + aoff + m * 2048 + k * 1024); } while (0)
; #define PG8_LDB(dst, b, h) do { _Pragma("unroll") for (int n = 0; n < 2; ++n) _Pragma("unroll") for (int k = 0; k < 2; ++k) dst[n][k] = *(const PG8_LAS bf16x8*)(lds + PG8_SB(b, h) + boff + n * 2048 + k * 1024); } while (0)
; #define PG8_MMA(ai, bj, At, Bt) do { __builtin_amdgcn_s_setprio(1); _Pragma("unroll") for (int m = 0; m < 4; ++m) _Pragma("unroll") for (int n = 0; n < 2; ++n) _Pragma("unroll") for (int k = 0; k < 2; ++k) \
;         acc[ai][bj][m][n] = __builtin_amdgcn_mfma_f32_16x16x32_bf16(Bt[n][k], At[m][k], acc[ai][bj][m][n], 0, 0, 0); __builtin_amdgcn_s_setprio(0); } while (0)
; #define PG8_WAIT_V(n) asm volatile("s_waitcnt vmcnt(" #n ")" ::: "memory")
; #define PG8_WAIT_L(n) asm volatile("s_waitcnt lgkmcnt(" #n ")" ::: "memory")
; #define PG8_BAR __builtin_amdgcn_s_barrier()
; #define PG8_SCHED __builtin_amdgcn_sched_barrier(0)
; template <class Epi, class Sched, bool ALIGN_EPI = false, bool SP2 = false>
; __device__ __forceinline__ void gemm_phase(PG8_LAS unsigned char* lds, const Gemm g, const Sched& S, const Epi& E) {
;     ...
;             PG8_WAIT_V(8); PG8_WAIT_L(0); PG8_BAR; PG8_MMA(1, 0, At, B0); PG8_MMA(1, 1, At, B1); PG8_BAR; PG8_SCHED;
;             PG8_LDB(B0, 1, 0); PG8_LDB(B1, 1, 1); PG8_SCHED; PG8_LDA(At, 1, 0); PG8_STAGE(PG8_SA(0, 1), a2 + hstep, voffA);
	s_setprio 1
	s_waitcnt lgkmcnt(0)
	v_mfma_f32_16x16x32_bf16 v[62:65], v[130:133], v[204:207], v[62:65]
	v_mfma_f32_16x16x32_bf16 v[58:61], v[178:181], v[204:207], v[58:61]
	v_mfma_f32_16x16x32_bf16 v[46:49], v[130:133], v[212:215], v[46:49]
	v_mfma_f32_16x16x32_bf16 v[42:45], v[178:181], v[212:215], v[42:45]
	v_mfma_f32_16x16x32_bf16 v[30:33], v[130:133], v[220:223], v[30:33]
	v_mfma_f32_16x16x32_bf16 v[26:29], v[178:181], v[220:223], v[26:29]
	v_mfma_f32_16x16x32_bf16 v[14:17], v[130:133], v[228:231], v[14:17]
	v_mfma_f32_16x16x32_bf16 v[10:13], v[178:181], v[228:231], v[10:13]
	v_mfma_f32_16x16x32_bf16 v[62:65], v[134:137], v[208:211], v[62:65]
	v_mfma_f32_16x16x32_bf16 v[58:61], v[182:185], v[208:211], v[58:61]
	v_mfma_f32_16x16x32_bf16 v[46:49], v[134:137], v[216:219], v[46:49]
	v_mfma_f32_16x16x32_bf16 v[42:45], v[182:185], v[216:219], v[42:45]
	v_mfma_f32_16x16x32_bf16 v[30:33], v[134:137], v[224:227], v[30:33]
	v_mfma_f32_16x16x32_bf16 v[26:29], v[182:185], v[224:227], v[26:29]
	v_mfma_f32_16x16x32_bf16 v[14:17], v[134:137], v[232:235], v[14:17]
	v_mfma_f32_16x16x32_bf16 v[10:13], v[182:185], v[232:235], v[10:13]
	s_setprio 0
	s_setprio 1
	v_mfma_f32_16x16x32_bf16 v[54:57], v[186:189], v[204:207], v[54:57]
	v_mfma_f32_16x16x32_bf16 v[50:53], v[194:197], v[204:207], v[50:53]
	v_mfma_f32_16x16x32_bf16 v[38:41], v[186:189], v[212:215], v[38:41]
	v_mfma_f32_16x16x32_bf16 v[34:37], v[194:197], v[212:215], v[34:37]
	v_mfma_f32_16x16x32_bf16 v[22:25], v[186:189], v[220:223], v[22:25]
	v_mfma_f32_16x16x32_bf16 v[18:21], v[194:197], v[220:223], v[18:21]
	v_mfma_f32_16x16x32_bf16 v[6:9], v[186:189], v[228:231], v[6:9]
	v_mfma_f32_16x16x32_bf16 v[2:5], v[194:197], v[228:231], v[2:5]
	v_mfma_f32_16x16x32_bf16 v[54:57], v[190:193], v[208:211], v[54:57]
	v_mfma_f32_16x16x32_bf16 v[50:53], v[200:203], v[208:211], v[50:53]
	v_mfma_f32_16x16x32_bf16 v[38:41], v[190:193], v[216:219], v[38:41]
	v_mfma_f32_16x16x32_bf16 v[34:37], v[200:203], v[216:219], v[34:37]
	v_mfma_f32_16x16x32_bf16 v[22:25], v[190:193], v[224:227], v[22:25]
	v_mfma_f32_16x16x32_bf16 v[18:21], v[200:203], v[224:227], v[18:21]
	v_mfma_f32_16x16x32_bf16 v[6:9], v[190:193], v[232:235], v[6:9]
	v_mfma_f32_16x16x32_bf16 v[2:5], v[200:203], v[232:235], v[2:5]
	s_setprio 0
	s_barrier
	s_mov_b32 m0, s40
	s_nop 0
	global_load_lds_dwordx4 v[238:239], off
	s_mov_b32 m0, s41
	s_nop 0
	global_load_lds_dwordx4 v[240:241], off
	s_add_i32 s57, 0, 0x18000
	v_add_u32_e32 v146, s57, v159
	s_add_i32 s58, 0, 0x1c000
	ds_read_b128 v[130:133], v146
	ds_read_b128 v[134:137], v146 offset:1024
	ds_read_b128 v[178:181], v146 offset:2048
	ds_read_b128 v[182:185], v146 offset:3072
	v_add_u32_e32 v146, s58, v159
	ds_read_b128 v[186:189], v146
	ds_read_b128 v[190:193], v146 offset:1024
	ds_read_b128 v[194:197], v146 offset:2048
	ds_read_b128 v[200:203], v146 offset:3072
	s_add_u32 s38, s38, 0x100000
	s_addc_u32 s39, s39, 0
	s_mov_b32 m0, s42
	v_lshl_add_u64 v[242:243], s[38:39], 0, v[138:139]
	ds_read_b128 v[204:207], v172 offset:32768
	ds_read_b128 v[208:211], v172 offset:33792
	ds_read_b128 v[212:215], v172 offset:34816
	ds_read_b128 v[216:219], v172 offset:35840
	ds_read_b128 v[220:223], v172 offset:36864
	ds_read_b128 v[224:227], v172 offset:37888
	ds_read_b128 v[228:231], v172 offset:38912
	ds_read_b128 v[232:235], v172 offset:39936
	global_load_lds_dwordx4 v[242:243], off
	v_lshl_add_u64 v[242:243], s[38:39], 0, v[142:143]
	s_mov_b32 m0, s43
	s_nop 0
	global_load_lds_dwordx4 v[242:243], off
	s_waitcnt vmcnt(8)
	s_waitcnt lgkmcnt(0)
	s_barrier
; #define PG8_STAGE(bufoff, gbase, voff) do { _Pragma("unroll") for (int _i = 0; _i < 2; ++_i) \
;         __builtin_amdgcn_global_load_lds((const unsigned*)((const char*)(gbase) + (voff)[_i]), (PG8_LAS unsigned*)(lds + (bufoff) + ldsw + _i * 8192), 16, 0, 0); } while (0)
; #define PG8_LDA(dst, b, h) do { _Pragma("unroll") for (int m = 0; m < 4; ++m) _Pragma("unroll") for (int k = 0; k < 2; ++k) dst[m][k] = *(const PG8_LAS bf16x8*)(lds + PG8_SA(b, h) + aoff + m * 2048 + k * 1024); } while (0)
; #define PG8_MMA(ai, bj, At, Bt) do { __builtin_amdgcn_s_setprio(1); _Pragma("unroll") for (int m = 0; m < 4; ++m) _Pragma("unroll") for (int n = 0; n < 2; ++n) _Pragma("unroll") for (int k = 0; k < 2; ++k) \
;         acc[ai][bj][m][n] = __builtin_amdgcn_mfma_f32_16x16x32_bf16(Bt[n][k], At[m][k], acc[ai][bj][m][n], 0, 0, 0); __builtin_amdgcn_s_setprio(0); } while (0)
; #define PG8_WAIT_V(n) asm volatile("s_waitcnt vmcnt(" #n ")" ::: "memory")
; #define PG8_WAIT_L(n) asm volatile("s_waitcnt lgkmcnt(" #n ")" ::: "memory")
; #define PG8_BAR __builtin_amdgcn_s_barrier()
; #define PG8_SCHED __builtin_amdgcn_sched_barrier(0)
; template <class Epi, class Sched, bool ALIGN_EPI = false, bool SP2 = false>
; __device__ __forceinline__ void gemm_phase(PG8_LAS unsigned char* lds, const Gemm g, const Sched& S, const Epi& E) {
;     ...
;         for (int t = 0; t < nt; t += 2) {
;             const bool last = (t == nt - 2);
;             const char* a1 = cA + (size_t)(t + 1) * kstep;
;             const char* a2 = last ? nA : cA + (size_t)(t + 2) * kstep; const char* b2 = last ? nB : cB + (size_t)(t + 2) * kstep;
;     ...
;             PG8_WAIT_V(8); PG8_WAIT_L(0); PG8_BAR; PG8_MMA(0, 0, At, B0); PG8_MMA(0, 1, At, B1); PG8_BAR; PG8_SCHED;
;             PG8_LDA(At, 1, 1); PG8_STAGE(PG8_SB(1, 0), b3, voffB); PG8_STAGE(PG8_SB(1, 1), b3 + hstep, voffB); PG8_STAGE(PG8_SA(1, 0), a3, voffA);
;             PG8_WAIT_V(8); PG8_WAIT_L(0); PG8_BAR; PG8_MMA(1, 0, At, B0); PG8_MMA(1, 1, At, B1); PG8_BAR; PG8_SCHED;
	s_setprio 1
	s_waitcnt lgkmcnt(0)
	v_mfma_f32_16x16x32_bf16 v[126:129], v[130:133], v[204:207], v[126:129]
	v_mfma_f32_16x16x32_bf16 v[122:125], v[178:181], v[204:207], v[122:125]
	v_mfma_f32_16x16x32_bf16 v[110:113], v[130:133], v[212:215], v[110:113]
	v_mfma_f32_16x16x32_bf16 v[106:109], v[178:181], v[212:215], v[106:109]
	v_mfma_f32_16x16x32_bf16 v[94:97], v[130:133], v[220:223], v[94:97]
	v_mfma_f32_16x16x32_bf16 v[90:93], v[178:181], v[220:223], v[90:93]
	v_mfma_f32_16x16x32_bf16 v[78:81], v[130:133], v[228:231], v[78:81]
	v_mfma_f32_16x16x32_bf16 v[74:77], v[178:181], v[228:231], v[74:77]
	v_mfma_f32_16x16x32_bf16 v[126:129], v[134:137], v[208:211], v[126:129]
	v_mfma_f32_16x16x32_bf16 v[122:125], v[182:185], v[208:211], v[122:125]
	v_mfma_f32_16x16x32_bf16 v[110:113], v[134:137], v[216:219], v[110:113]
	v_mfma_f32_16x16x32_bf16 v[106:109], v[182:185], v[216:219], v[106:109]
	v_mfma_f32_16x16x32_bf16 v[94:97], v[134:137], v[224:227], v[94:97]
	v_mfma_f32_16x16x32_bf16 v[90:93], v[182:185], v[224:227], v[90:93]
	v_mfma_f32_16x16x32_bf16 v[78:81], v[134:137], v[232:235], v[78:81]
	v_mfma_f32_16x16x32_bf16 v[74:77], v[182:185], v[232:235], v[74:77]
	s_setprio 0
	s_setprio 1
	v_mfma_f32_16x16x32_bf16 v[118:121], v[186:189], v[204:207], v[118:121]
	v_mfma_f32_16x16x32_bf16 v[114:117], v[194:197], v[204:207], v[114:117]
	v_mfma_f32_16x16x32_bf16 v[102:105], v[186:189], v[212:215], v[102:105]
	v_mfma_f32_16x16x32_bf16 v[98:101], v[194:197], v[212:215], v[98:101]
	v_mfma_f32_16x16x32_bf16 v[86:89], v[186:189], v[220:223], v[86:89]
	v_mfma_f32_16x16x32_bf16 v[82:85], v[194:197], v[220:223], v[82:85]
	v_mfma_f32_16x16x32_bf16 v[70:73], v[186:189], v[228:231], v[70:73]
	v_mfma_f32_16x16x32_bf16 v[66:69], v[194:197], v[228:231], v[66:69]
	v_mfma_f32_16x16x32_bf16 v[118:121], v[190:193], v[208:211], v[118:121]
	v_mfma_f32_16x16x32_bf16 v[114:117], v[200:203], v[208:211], v[114:117]
	v_mfma_f32_16x16x32_bf16 v[102:105], v[190:193], v[216:219], v[102:105]
	v_mfma_f32_16x16x32_bf16 v[98:101], v[200:203], v[216:219], v[98:101]
	v_mfma_f32_16x16x32_bf16 v[86:89], v[190:193], v[224:227], v[86:89]
	v_mfma_f32_16x16x32_bf16 v[82:85], v[200:203], v[224:227], v[82:85]
	v_mfma_f32_16x16x32_bf16 v[70:73], v[190:193], v[232:235], v[70:73]
	v_mfma_f32_16x16x32_bf16 v[66:69], v[200:203], v[232:235], v[66:69]
	s_setprio 0
	s_barrier
	s_add_i32 s38, s57, s33
	v_lshl_add_u64 v[156:157], v[156:157], 0, s[10:11]
	s_mov_b32 m0, s38
	ds_read_b128 v[204:207], v172 offset:49152
	ds_read_b128 v[208:211], v172 offset:50176
	ds_read_b128 v[212:215], v172 offset:51200
	ds_read_b128 v[216:219], v172 offset:52224
	ds_read_b128 v[220:223], v172 offset:53248
	ds_read_b128 v[224:227], v172 offset:54272
	ds_read_b128 v[228:231], v172 offset:55296
	ds_read_b128 v[232:235], v172 offset:56320
	global_load_lds_dwordx4 v[156:157], off
	s_add_i32 m0, s38, 0x2000
	s_add_u32 s36, s36, 0x100080
	v_lshl_add_u64 v[156:157], v[236:237], 0, s[10:11]
	s_addc_u32 s37, s37, 0
	s_add_i32 s38, s58, s33
	global_load_lds_dwordx4 v[156:157], off
	v_lshl_add_u64 v[156:157], s[36:37], 0, v[140:141]
	s_mov_b32 m0, s38
	s_nop 0
	global_load_lds_dwordx4 v[156:157], off
	v_lshl_add_u64 v[156:157], s[36:37], 0, v[144:145]
	s_add_i32 m0, s38, 0x2000
	s_nop 0
	global_load_lds_dwordx4 v[156:157], off
	s_waitcnt vmcnt(6)
	s_waitcnt lgkmcnt(0)
	s_barrier
	s_setprio 1
	s_waitcnt lgkmcnt(0)
	v_mfma_f32_16x16x32_bf16 v[62:65], v[130:133], v[204:207], v[62:65]
	v_mfma_f32_16x16x32_bf16 v[58:61], v[178:181], v[204:207], v[58:61]
	v_mfma_f32_16x16x32_bf16 v[46:49], v[130:133], v[212:215], v[46:49]
	v_mfma_f32_16x16x32_bf16 v[42:45], v[178:181], v[212:215], v[42:45]
	v_mfma_f32_16x16x32_bf16 v[30:33], v[130:133], v[220:223], v[30:33]
	v_mfma_f32_16x16x32_bf16 v[26:29], v[178:181], v[220:223], v[26:29]
	v_mfma_f32_16x16x32_bf16 v[14:17], v[130:133], v[228:231], v[14:17]
	v_mfma_f32_16x16x32_bf16 v[10:13], v[178:181], v[228:231], v[10:13]
	v_mfma_f32_16x16x32_bf16 v[62:65], v[134:137], v[208:211], v[62:65]
	v_mfma_f32_16x16x32_bf16 v[58:61], v[182:185], v[208:211], v[58:61]
	v_mfma_f32_16x16x32_bf16 v[46:49], v[134:137], v[216:219], v[46:49]
	v_mfma_f32_16x16x32_bf16 v[42:45], v[182:185], v[216:219], v[42:45]
	v_mfma_f32_16x16x32_bf16 v[30:33], v[134:137], v[224:227], v[30:33]
	v_mfma_f32_16x16x32_bf16 v[26:29], v[182:185], v[224:227], v[26:29]
	v_mfma_f32_16x16x32_bf16 v[14:17], v[134:137], v[232:235], v[14:17]
	v_mfma_f32_16x16x32_bf16 v[10:13], v[182:185], v[232:235], v[10:13]
	s_setprio 0
	s_setprio 1
	v_mfma_f32_16x16x32_bf16 v[54:57], v[186:189], v[204:207], v[54:57]
	v_mfma_f32_16x16x32_bf16 v[50:53], v[194:197], v[204:207], v[50:53]
	v_mfma_f32_16x16x32_bf16 v[38:41], v[186:189], v[212:215], v[38:41]
	v_mfma_f32_16x16x32_bf16 v[34:37], v[194:197], v[212:215], v[34:37]
	v_mfma_f32_16x16x32_bf16 v[22:25], v[186:189], v[220:223], v[22:25]
	v_mfma_f32_16x16x32_bf16 v[18:21], v[194:197], v[220:223], v[18:21]
	v_mfma_f32_16x16x32_bf16 v[6:9], v[186:189], v[228:231], v[6:9]
	v_mfma_f32_16x16x32_bf16 v[2:5], v[194:197], v[228:231], v[2:5]
	v_mfma_f32_16x16x32_bf16 v[54:57], v[190:193], v[208:211], v[54:57]
	v_mfma_f32_16x16x32_bf16 v[50:53], v[200:203], v[208:211], v[50:53]
	v_mfma_f32_16x16x32_bf16 v[38:41], v[190:193], v[216:219], v[38:41]
	v_mfma_f32_16x16x32_bf16 v[34:37], v[200:203], v[216:219], v[34:37]
	v_mfma_f32_16x16x32_bf16 v[22:25], v[190:193], v[224:227], v[22:25]
	v_mfma_f32_16x16x32_bf16 v[18:21], v[200:203], v[224:227], v[18:21]
	v_mfma_f32_16x16x32_bf16 v[6:9], v[190:193], v[232:235], v[6:9]
	v_mfma_f32_16x16x32_bf16 v[2:5], v[200:203], v[232:235], v[2:5]
	s_setprio 0
	s_barrier
	s_add_i32 s56, s56, 2
	s_add_u32 s34, s34, 0x100
	s_addc_u32 s35, s35, 0
	s_add_u32 s54, s54, 0x100
	s_addc_u32 s55, s55, 0
	s_cmp_gt_u32 s56, 61
	s_cbranch_scc0 .LBB0_180
	s_and_b64 vcc, exec, s[12:13]
	s_cbranch_vccz .LBB0_183
	s_barrier

; #define PG8_STAGE(bufoff, gbase, voff) do { _Pragma("unroll") for (int _i = 0; _i < 2; ++_i) \
;         __builtin_amdgcn_global_load_lds((const unsigned*)((const char*)(gbase) + (voff)[_i]), (PG8_LAS unsigned*)(lds + (bufoff) + ldsw + _i * 8192), 16, 0, 0); } while (0)
; #define PG8_LDA(dst, b, h) do { _Pragma("unroll") for (int m = 0; m < 4; ++m) _Pragma("unroll") for (int k = 0; k < 2; ++k) dst[m][k] = *(const PG8_LAS bf16x8*)(lds + PG8_SA(b, h) + aoff + m * 2048 + k * 1024); } while (0)
; #define PG8_LDB(dst, b, h) do { _Pragma("unroll") for (int n = 0; n < 2; ++n) _Pragma("unroll") for (int k = 0; k < 2; ++k) dst[n][k] = *(const PG8_LAS bf16x8*)(lds + PG8_SB(b, h) + boff + n * 2048 + k * 1024); } while (0)
; #define PG8_MMA(ai, bj, At, Bt) do { __builtin_amdgcn_s_setprio(1); _Pragma("unroll") for (int m = 0; m < 4; ++m) _Pragma("unroll") for (int n = 0; n < 2; ++n) _Pragma("unroll") for (int k = 0; k < 2; ++k) \
;         acc[ai][bj][m][n] = __builtin_amdgcn_mfma_f32_16x16x32_bf16(Bt[n][k], At[m][k], acc[ai][bj][m][n], 0, 0, 0); __builtin_amdgcn_s_setprio(0); } while (0)
; #define PG8_WAIT_V(n) asm volatile("s_waitcnt vmcnt(" #n ")" ::: "memory")
; #define PG8_WAIT_L(n) asm volatile("s_waitcnt lgkmcnt(" #n ")" ::: "memory")
; #define PG8_BAR __builtin_amdgcn_s_barrier()
; #define PG8_SCHED __builtin_amdgcn_sched_barrier(0)
; template <class Epi, class Sched, bool ALIGN_EPI = false, bool SP2 = false>
; __device__ __forceinline__ void gemm_phase(PG8_LAS unsigned char* lds, const Gemm g, const Sched& S, const Epi& E) {
;     ...
;             PG8_LDB(B0, 0, 0); PG8_LDB(B1, 0, 1); PG8_SCHED; PG8_LDA(At, 0, 0); PG8_STAGE(PG8_SA(1, 1), a1 + hstep, voffA);
;             PG8_WAIT_V(8); PG8_WAIT_L(0); PG8_BAR; PG8_MMA(0, 0, At, B0); PG8_MMA(0, 1, At, B1); PG8_BAR; PG8_SCHED;
;             PG8_LDA(At, 0, 1); PG8_STAGE(PG8_SB(0, 0), b2, voffB); PG8_STAGE(PG8_SB(0, 1), b2 + hstep, voffB); PG8_STAGE(PG8_SA(0, 0), a2, voffA);
;             PG8_WAIT_V(8); PG8_WAIT_L(0); PG8_BAR; PG8_MMA(1, 0, At, B0); PG8_MMA(1, 1, At, B1); PG8_BAR; PG8_SCHED;
.LBB0_857:
	s_add_u32 s34, s30, 0xfff80000
	s_addc_u32 s35, s31, -1
	v_lshl_add_u64 v[196:197], s[34:35], 0, v[150:151]
	s_mov_b32 m0, s43
	s_nop 0
	global_load_lds_dwordx4 v[196:197], off
	v_lshl_add_u64 v[196:197], s[34:35], 0, v[154:155]
	s_mov_b32 m0, s44
	s_nop 0
	global_load_lds_dwordx4 v[196:197], off
	s_add_u32 s34, s34, 0x80
	s_addc_u32 s35, s35, 0
	ds_read_b128 v[130:133], v180
	ds_read_b128 v[134:137], v180 offset:1024
	ds_read_b128 v[138:141], v180 offset:2048
	ds_read_b128 v[142:145], v180 offset:3072
	ds_read_b128 v[146:149], v181
	ds_read_b128 v[166:169], v181 offset:1024
	ds_read_b128 v[170:173], v181 offset:2048
	ds_read_b128 v[174:177], v181 offset:3072
	s_cmp_eq_u32 s56, 28
	s_cselect_b32 s37, s15, s35
	s_cselect_b32 s36, s50, s34
	s_cselect_b32 s35, s13, s53
	s_cselect_b32 s34, s51, s52
	v_lshl_add_u64 v[196:197], s[30:31], 0, v[158:159]
	s_add_i32 m0, s29, 0xc000
	ds_read_b128 v[184:187], v182
	ds_read_b128 v[188:191], v182 offset:1024
	ds_read_b128 v[192:195], v182 offset:2048
	ds_read_b128 v[200:203], v182 offset:3072
	ds_read_b128 v[204:207], v182 offset:4096
	ds_read_b128 v[208:211], v182 offset:5120
	ds_read_b128 v[212:215], v182 offset:6144
	ds_read_b128 v[216:219], v182 offset:7168
	global_load_lds_dwordx4 v[196:197], off
	v_lshl_add_u64 v[196:197], s[30:31], 0, v[160:161]
	s_add_i32 m0, s29, 0xe000
	s_nop 0
	global_load_lds_dwordx4 v[196:197], off
	s_waitcnt vmcnt(8)
	s_waitcnt lgkmcnt(0)
	s_barrier
	s_setprio 1
	s_waitcnt lgkmcnt(0)
	v_mfma_f32_16x16x32_bf16 v[126:129], v[130:133], v[184:187], v[126:129]
	v_mfma_f32_16x16x32_bf16 v[122:125], v[138:141], v[184:187], v[122:125]
	v_mfma_f32_16x16x32_bf16 v[110:113], v[130:133], v[192:195], v[110:113]
	v_mfma_f32_16x16x32_bf16 v[106:109], v[138:141], v[192:195], v[106:109]
	v_mfma_f32_16x16x32_bf16 v[94:97], v[130:133], v[204:207], v[94:97]
	v_mfma_f32_16x16x32_bf16 v[90:93], v[138:141], v[204:207], v[90:93]
	v_mfma_f32_16x16x32_bf16 v[78:81], v[130:133], v[212:215], v[78:81]
	v_mfma_f32_16x16x32_bf16 v[74:77], v[138:141], v[212:215], v[74:77]
	v_mfma_f32_16x16x32_bf16 v[126:129], v[134:137], v[188:191], v[126:129]
	v_mfma_f32_16x16x32_bf16 v[122:125], v[142:145], v[188:191], v[122:125]
	v_mfma_f32_16x16x32_bf16 v[110:113], v[134:137], v[200:203], v[110:113]
	v_mfma_f32_16x16x32_bf16 v[106:109], v[142:145], v[200:203], v[106:109]
	v_mfma_f32_16x16x32_bf16 v[94:97], v[134:137], v[208:211], v[94:97]
	v_mfma_f32_16x16x32_bf16 v[90:93], v[142:145], v[208:211], v[90:93]
	v_mfma_f32_16x16x32_bf16 v[78:81], v[134:137], v[216:219], v[78:81]
	v_mfma_f32_16x16x32_bf16 v[74:77], v[142:145], v[216:219], v[74:77]
	s_setprio 0
	s_setprio 1
	v_mfma_f32_16x16x32_bf16 v[118:121], v[146:149], v[184:187], v[118:121]
	v_mfma_f32_16x16x32_bf16 v[114:117], v[170:173], v[184:187], v[114:117]
	v_mfma_f32_16x16x32_bf16 v[102:105], v[146:149], v[192:195], v[102:105]
	v_mfma_f32_16x16x32_bf16 v[98:101], v[170:173], v[192:195], v[98:101]
	v_mfma_f32_16x16x32_bf16 v[86:89], v[146:149], v[204:207], v[86:89]
	v_mfma_f32_16x16x32_bf16 v[82:85], v[170:173], v[204:207], v[82:85]
	v_mfma_f32_16x16x32_bf16 v[70:73], v[146:149], v[212:215], v[70:73]
	v_mfma_f32_16x16x32_bf16 v[66:69], v[170:173], v[212:215], v[66:69]
	v_mfma_f32_16x16x32_bf16 v[118:121], v[166:169], v[188:191], v[118:121]
	v_mfma_f32_16x16x32_bf16 v[114:117], v[174:177], v[188:191], v[114:117]
	v_mfma_f32_16x16x32_bf16 v[102:105], v[166:169], v[200:203], v[102:105]
	v_mfma_f32_16x16x32_bf16 v[98:101], v[174:177], v[200:203], v[98:101]
	v_mfma_f32_16x16x32_bf16 v[86:89], v[166:169], v[208:211], v[86:89]
	v_mfma_f32_16x16x32_bf16 v[82:85], v[174:177], v[208:211], v[82:85]
	v_mfma_f32_16x16x32_bf16 v[70:73], v[166:169], v[216:219], v[70:73]
	v_mfma_f32_16x16x32_bf16 v[66:69], v[174:177], v[216:219], v[66:69]
	s_setprio 0
	s_barrier
	s_add_i32 s57, s46, s38
	v_lshl_add_u64 v[196:197], s[34:35], 0, v[152:153]
	s_mov_b32 m0, s57
	ds_read_b128 v[184:187], v182 offset:16384
	ds_read_b128 v[188:191], v182 offset:17408
	ds_read_b128 v[192:195], v182 offset:18432
	ds_read_b128 v[200:203], v182 offset:19456
	ds_read_b128 v[204:207], v182 offset:20480
	ds_read_b128 v[208:211], v182 offset:21504
	ds_read_b128 v[212:215], v182 offset:22528
	ds_read_b128 v[216:219], v182 offset:23552
	global_load_lds_dwordx4 v[196:197], off
	s_add_i32 m0, s57, 0x2000
	s_add_u32 s58, s34, 0x80000
	v_lshl_add_u64 v[220:221], s[34:35], 0, v[156:157]
	s_addc_u32 s59, s35, 0
	s_add_i32 s57, s47, s38
	global_load_lds_dwordx4 v[220:221], off
	v_lshl_add_u64 v[222:223], s[58:59], 0, v[152:153]
	s_mov_b32 m0, s57
	v_lshl_add_u64 v[224:225], s[36:37], 0, v[154:155]
	global_load_lds_dwordx4 v[222:223], off
	v_lshl_add_u64 v[222:223], s[58:59], 0, v[156:157]
	s_add_i32 m0, s57, 0x2000
	s_nop 0
	global_load_lds_dwordx4 v[222:223], off
	v_lshl_add_u64 v[222:223], s[36:37], 0, v[150:151]
	s_waitcnt vmcnt(6)
	s_waitcnt lgkmcnt(0)
	s_barrier
; #define PG8_STAGE(bufoff, gbase, voff) do { _Pragma("unroll") for (int _i = 0; _i < 2; ++_i) \
;         __builtin_amdgcn_global_load_lds((const unsigned*)((const char*)(gbase) + (voff)[_i]), (PG8_LAS unsigned*)(lds + (bufoff) + ldsw + _i * 8192), 16, 0, 0); } while (0)
; #define PG8_LDA(dst, b, h) do { _Pragma("unroll") for (int m = 0; m < 4; ++m) _Pragma("unroll") for (int k = 0; k < 2; ++k) dst[m][k] = *(const PG8_LAS bf16x8*)(lds + PG8_SA(b, h) + aoff + m * 2048 + k * 1024); } while (0)
; #define PG8_LDB(dst, b, h) do { _Pragma("unroll") for (int n = 0; n < 2; ++n) _Pragma("unroll") for (int k = 0; k < 2; ++k) dst[n][k] = *(const PG8_LAS bf16x8*)(lds + PG8_SB(b, h) + boff + n * 2048 + k * 1024); } while (0)
; #define PG8_MMA(ai, bj, At, Bt) do { __builtin_amdgcn_s_setprio(1); _Pragma("unroll") for (int m = 0; m < 4; ++m) _Pragma("unroll") for (int n = 0; n < 2; ++n) _Pragma("unroll") for (int k = 0; k < 2; ++k) \
;         acc[ai][bj][m][n] = __builtin_amdgcn_mfma_f32_16x16x32_bf16(Bt[n][k], At[m][k], acc[ai][bj][m][n], 0, 0, 0); __builtin_amdgcn_s_setprio(0); } while (0)
; #define PG8_WAIT_V(n) asm volatile("s_waitcnt vmcnt(" #n ")" ::: "memory")
; #define PG8_WAIT_L(n) asm volatile("s_waitcnt lgkmcnt(" #n ")" ::: "memory")
; #define PG8_BAR __builtin_amdgcn_s_barrier()
; #define PG8_SCHED __builtin_amdgcn_sched_barrier(0)
; template <class Epi, class Sched, bool ALIGN_EPI = false, bool SP2 = false>
; __device__ __forceinline__ void gemm_phase(PG8_LAS unsigned char* lds, const Gemm g, const Sched& S, const Epi& E) {
;     ...
;             PG8_WAIT_V(8); PG8_WAIT_L(0); PG8_BAR; PG8_MMA(1, 0, At, B0); PG8_MMA(1, 1, At, B1); PG8_BAR; PG8_SCHED;
;             PG8_LDB(B0, 1, 0); PG8_LDB(B1, 1, 1); PG8_SCHED; PG8_LDA(At, 1, 0); PG8_STAGE(PG8_SA(0, 1), a2 + hstep, voffA);
	s_setprio 1
	s_waitcnt lgkmcnt(0)
	v_mfma_f32_16x16x32_bf16 v[62:65], v[130:133], v[184:187], v[62:65]
	v_mfma_f32_16x16x32_bf16 v[58:61], v[138:141], v[184:187], v[58:61]
	v_mfma_f32_16x16x32_bf16 v[46:49], v[130:133], v[192:195], v[46:49]
	v_mfma_f32_16x16x32_bf16 v[42:45], v[138:141], v[192:195], v[42:45]
	v_mfma_f32_16x16x32_bf16 v[30:33], v[130:133], v[204:207], v[30:33]
	v_mfma_f32_16x16x32_bf16 v[26:29], v[138:141], v[204:207], v[26:29]
	v_mfma_f32_16x16x32_bf16 v[14:17], v[130:133], v[212:215], v[14:17]
	v_mfma_f32_16x16x32_bf16 v[10:13], v[138:141], v[212:215], v[10:13]
	v_mfma_f32_16x16x32_bf16 v[62:65], v[134:137], v[188:191], v[62:65]
	v_mfma_f32_16x16x32_bf16 v[58:61], v[142:145], v[188:191], v[58:61]
	v_mfma_f32_16x16x32_bf16 v[46:49], v[134:137], v[200:203], v[46:49]
	v_mfma_f32_16x16x32_bf16 v[42:45], v[142:145], v[200:203], v[42:45]
	v_mfma_f32_16x16x32_bf16 v[30:33], v[134:137], v[208:211], v[30:33]
	v_mfma_f32_16x16x32_bf16 v[26:29], v[142:145], v[208:211], v[26:29]
	v_mfma_f32_16x16x32_bf16 v[14:17], v[134:137], v[216:219], v[14:17]
	v_mfma_f32_16x16x32_bf16 v[10:13], v[142:145], v[216:219], v[10:13]
	s_setprio 0
	s_setprio 1
	v_mfma_f32_16x16x32_bf16 v[54:57], v[146:149], v[184:187], v[54:57]
	v_mfma_f32_16x16x32_bf16 v[50:53], v[170:173], v[184:187], v[50:53]
	v_mfma_f32_16x16x32_bf16 v[38:41], v[146:149], v[192:195], v[38:41]
	v_mfma_f32_16x16x32_bf16 v[34:37], v[170:173], v[192:195], v[34:37]
	v_mfma_f32_16x16x32_bf16 v[22:25], v[146:149], v[204:207], v[22:25]
	v_mfma_f32_16x16x32_bf16 v[18:21], v[170:173], v[204:207], v[18:21]
	v_mfma_f32_16x16x32_bf16 v[6:9], v[146:149], v[212:215], v[6:9]
	v_mfma_f32_16x16x32_bf16 v[2:5], v[170:173], v[212:215], v[2:5]
	v_mfma_f32_16x16x32_bf16 v[54:57], v[166:169], v[188:191], v[54:57]
	v_mfma_f32_16x16x32_bf16 v[50:53], v[174:177], v[188:191], v[50:53]
	v_mfma_f32_16x16x32_bf16 v[38:41], v[166:169], v[200:203], v[38:41]
	v_mfma_f32_16x16x32_bf16 v[34:37], v[174:177], v[200:203], v[34:37]
	v_mfma_f32_16x16x32_bf16 v[22:25], v[166:169], v[208:211], v[22:25]
	v_mfma_f32_16x16x32_bf16 v[18:21], v[174:177], v[208:211], v[18:21]
	v_mfma_f32_16x16x32_bf16 v[6:9], v[166:169], v[216:219], v[6:9]
	v_mfma_f32_16x16x32_bf16 v[2:5], v[174:177], v[216:219], v[2:5]
	s_setprio 0
	s_barrier
	s_mov_b32 m0, s29
	s_nop 0
	global_load_lds_dwordx4 v[222:223], off
	s_mov_b32 m0, s39
	s_nop 0
	global_load_lds_dwordx4 v[224:225], off
	s_add_i32 s57, 0, 0x18000
	s_add_i32 s58, 0, 0x1c000
	v_add_u32_e32 v142, s57, v178
	v_add_u32_e32 v174, s58, v178
	ds_read_b128 v[130:133], v142
	ds_read_b128 v[134:137], v142 offset:1024
	ds_read_b128 v[138:141], v142 offset:2048
	ds_read_b128 v[142:145], v142 offset:3072
	ds_read_b128 v[146:149], v174
	ds_read_b128 v[166:169], v174 offset:1024
	ds_read_b128 v[170:173], v174 offset:2048
	ds_read_b128 v[174:177], v174 offset:3072
	s_add_u32 s36, s36, 0x80000
	s_addc_u32 s37, s37, 0
	s_mov_b32 m0, s40
	v_lshl_add_u64 v[226:227], s[36:37], 0, v[150:151]
	ds_read_b128 v[184:187], v182 offset:32768
	ds_read_b128 v[188:191], v182 offset:33792
	ds_read_b128 v[192:195], v182 offset:34816
	ds_read_b128 v[200:203], v182 offset:35840
	ds_read_b128 v[204:207], v182 offset:36864
	ds_read_b128 v[208:211], v182 offset:37888
	ds_read_b128 v[212:215], v182 offset:38912
	ds_read_b128 v[216:219], v182 offset:39936
	global_load_lds_dwordx4 v[226:227], off
	v_lshl_add_u64 v[226:227], s[36:37], 0, v[154:155]
	s_mov_b32 m0, s41
	s_nop 0
	global_load_lds_dwordx4 v[226:227], off
	s_waitcnt vmcnt(8)
	s_waitcnt lgkmcnt(0)
	s_barrier
; #define PG8_STAGE(bufoff, gbase, voff) do { _Pragma("unroll") for (int _i = 0; _i < 2; ++_i) \
;         __builtin_amdgcn_global_load_lds((const unsigned*)((const char*)(gbase) + (voff)[_i]), (PG8_LAS unsigned*)(lds + (bufoff) + ldsw + _i * 8192), 16, 0, 0); } while (0)
; #define PG8_LDA(dst, b, h) do { _Pragma("unroll") for (int m = 0; m < 4; ++m) _Pragma("unroll") for (int k = 0; k < 2; ++k) dst[m][k] = *(const PG8_LAS bf16x8*)(lds + PG8_SA(b, h) + aoff + m * 2048 + k * 1024); } while (0)
; #define PG8_MMA(ai, bj, At, Bt) do { __builtin_amdgcn_s_setprio(1); _Pragma("unroll") for (int m = 0; m < 4; ++m) _Pragma("unroll") for (int n = 0; n < 2; ++n) _Pragma("unroll") for (int k = 0; k < 2; ++k) \
;         acc[ai][bj][m][n] = __builtin_amdgcn_mfma_f32_16x16x32_bf16(Bt[n][k], At[m][k], acc[ai][bj][m][n], 0, 0, 0); __builtin_amdgcn_s_setprio(0); } while (0)
; #define PG8_WAIT_V(n) asm volatile("s_waitcnt vmcnt(" #n ")" ::: "memory")
; #define PG8_WAIT_L(n) asm volatile("s_waitcnt lgkmcnt(" #n ")" ::: "memory")
; #define PG8_BAR __builtin_amdgcn_s_barrier()
; #define PG8_SCHED __builtin_amdgcn_sched_barrier(0)
; template <class Epi, class Sched, bool ALIGN_EPI = false, bool SP2 = false>
; __device__ __forceinline__ void gemm_phase(PG8_LAS unsigned char* lds, const Gemm g, const Sched& S, const Epi& E) {
;     ...
;         for (int t = 0; t < nt; t += 2) {
;             const bool last = (t == nt - 2);
;             const char* a1 = cA + (size_t)(t + 1) * kstep;
;             const char* a2 = last ? nA : cA + (size_t)(t + 2) * kstep; const char* b2 = last ? nB : cB + (size_t)(t + 2) * kstep;
;     ...
;             PG8_WAIT_V(8); PG8_WAIT_L(0); PG8_BAR; PG8_MMA(0, 0, At, B0); PG8_MMA(0, 1, At, B1); PG8_BAR; PG8_SCHED;
;             PG8_LDA(At, 1, 1); PG8_STAGE(PG8_SB(1, 0), b3, voffB); PG8_STAGE(PG8_SB(1, 1), b3 + hstep, voffB); PG8_STAGE(PG8_SA(1, 0), a3, voffA);
;             PG8_WAIT_V(8); PG8_WAIT_L(0); PG8_BAR; PG8_MMA(1, 0, At, B0); PG8_MMA(1, 1, At, B1); PG8_BAR; PG8_SCHED;
	s_setprio 1
	s_waitcnt lgkmcnt(0)
	v_mfma_f32_16x16x32_bf16 v[126:129], v[130:133], v[184:187], v[126:129]
	v_mfma_f32_16x16x32_bf16 v[122:125], v[138:141], v[184:187], v[122:125]
	v_mfma_f32_16x16x32_bf16 v[110:113], v[130:133], v[192:195], v[110:113]
	v_mfma_f32_16x16x32_bf16 v[106:109], v[138:141], v[192:195], v[106:109]
	v_mfma_f32_16x16x32_bf16 v[94:97], v[130:133], v[204:207], v[94:97]
	v_mfma_f32_16x16x32_bf16 v[90:93], v[138:141], v[204:207], v[90:93]
	v_mfma_f32_16x16x32_bf16 v[78:81], v[130:133], v[212:215], v[78:81]
	v_mfma_f32_16x16x32_bf16 v[74:77], v[138:141], v[212:215], v[74:77]
	v_mfma_f32_16x16x32_bf16 v[126:129], v[134:137], v[188:191], v[126:129]
	v_mfma_f32_16x16x32_bf16 v[122:125], v[142:145], v[188:191], v[122:125]
	v_mfma_f32_16x16x32_bf16 v[110:113], v[134:137], v[200:203], v[110:113]
	v_mfma_f32_16x16x32_bf16 v[106:109], v[142:145], v[200:203], v[106:109]
	v_mfma_f32_16x16x32_bf16 v[94:97], v[134:137], v[208:211], v[94:97]
	v_mfma_f32_16x16x32_bf16 v[90:93], v[142:145], v[208:211], v[90:93]
	v_mfma_f32_16x16x32_bf16 v[78:81], v[134:137], v[216:219], v[78:81]
	v_mfma_f32_16x16x32_bf16 v[74:77], v[142:145], v[216:219], v[74:77]
	s_setprio 0
	s_setprio 1
	v_mfma_f32_16x16x32_bf16 v[118:121], v[146:149], v[184:187], v[118:121]
	v_mfma_f32_16x16x32_bf16 v[114:117], v[170:173], v[184:187], v[114:117]
	v_mfma_f32_16x16x32_bf16 v[102:105], v[146:149], v[192:195], v[102:105]
	v_mfma_f32_16x16x32_bf16 v[98:101], v[170:173], v[192:195], v[98:101]
	v_mfma_f32_16x16x32_bf16 v[86:89], v[146:149], v[204:207], v[86:89]
	v_mfma_f32_16x16x32_bf16 v[82:85], v[170:173], v[204:207], v[82:85]
	v_mfma_f32_16x16x32_bf16 v[70:73], v[146:149], v[212:215], v[70:73]
	v_mfma_f32_16x16x32_bf16 v[66:69], v[170:173], v[212:215], v[66:69]
	v_mfma_f32_16x16x32_bf16 v[118:121], v[166:169], v[188:191], v[118:121]
	v_mfma_f32_16x16x32_bf16 v[114:117], v[174:177], v[188:191], v[114:117]
	v_mfma_f32_16x16x32_bf16 v[102:105], v[166:169], v[200:203], v[102:105]
	v_mfma_f32_16x16x32_bf16 v[98:101], v[174:177], v[200:203], v[98:101]
	v_mfma_f32_16x16x32_bf16 v[86:89], v[166:169], v[208:211], v[86:89]
	v_mfma_f32_16x16x32_bf16 v[82:85], v[174:177], v[208:211], v[82:85]
	v_mfma_f32_16x16x32_bf16 v[70:73], v[166:169], v[216:219], v[70:73]
	v_mfma_f32_16x16x32_bf16 v[66:69], v[174:177], v[216:219], v[66:69]
	s_setprio 0
	s_barrier
	s_add_i32 s36, s57, s38
	v_lshl_add_u64 v[196:197], v[196:197], 0, s[8:9]
	s_mov_b32 m0, s36
	ds_read_b128 v[184:187], v182 offset:49152
	ds_read_b128 v[188:191], v182 offset:50176
	ds_read_b128 v[192:195], v182 offset:51200
	ds_read_b128 v[200:203], v182 offset:52224
	ds_read_b128 v[204:207], v182 offset:53248
	ds_read_b128 v[208:211], v182 offset:54272
	ds_read_b128 v[212:215], v182 offset:55296
	ds_read_b128 v[216:219], v182 offset:56320
	global_load_lds_dwordx4 v[196:197], off
	s_add_i32 m0, s36, 0x2000
	s_add_u32 s34, s34, 0x80080
	v_lshl_add_u64 v[196:197], v[220:221], 0, s[8:9]
	s_addc_u32 s35, s35, 0
	s_add_i32 s36, s58, s38
	global_load_lds_dwordx4 v[196:197], off
	v_lshl_add_u64 v[196:197], s[34:35], 0, v[152:153]
	s_mov_b32 m0, s36
	s_nop 0
	global_load_lds_dwordx4 v[196:197], off
	v_lshl_add_u64 v[196:197], s[34:35], 0, v[156:157]
	s_add_i32 m0, s36, 0x2000
	s_nop 0
	global_load_lds_dwordx4 v[196:197], off
	s_waitcnt vmcnt(6)
	s_waitcnt lgkmcnt(0)
	s_barrier
	s_setprio 1
	s_waitcnt lgkmcnt(0)
	v_mfma_f32_16x16x32_bf16 v[62:65], v[130:133], v[184:187], v[62:65]
	v_mfma_f32_16x16x32_bf16 v[58:61], v[138:141], v[184:187], v[58:61]
	v_mfma_f32_16x16x32_bf16 v[46:49], v[130:133], v[192:195], v[46:49]
	v_mfma_f32_16x16x32_bf16 v[42:45], v[138:141], v[192:195], v[42:45]
	v_mfma_f32_16x16x32_bf16 v[30:33], v[130:133], v[204:207], v[30:33]
	v_mfma_f32_16x16x32_bf16 v[26:29], v[138:141], v[204:207], v[26:29]
	v_mfma_f32_16x16x32_bf16 v[14:17], v[130:133], v[212:215], v[14:17]
	v_mfma_f32_16x16x32_bf16 v[10:13], v[138:141], v[212:215], v[10:13]
	v_mfma_f32_16x16x32_bf16 v[62:65], v[134:137], v[188:191], v[62:65]
	v_mfma_f32_16x16x32_bf16 v[58:61], v[142:145], v[188:191], v[58:61]
	v_mfma_f32_16x16x32_bf16 v[46:49], v[134:137], v[200:203], v[46:49]
	v_mfma_f32_16x16x32_bf16 v[42:45], v[142:145], v[200:203], v[42:45]
	v_mfma_f32_16x16x32_bf16 v[30:33], v[134:137], v[208:211], v[30:33]
	v_mfma_f32_16x16x32_bf16 v[26:29], v[142:145], v[208:211], v[26:29]
	v_mfma_f32_16x16x32_bf16 v[14:17], v[134:137], v[216:219], v[14:17]
	v_mfma_f32_16x16x32_bf16 v[10:13], v[142:145], v[216:219], v[10:13]
	s_setprio 0
	s_setprio 1
	v_mfma_f32_16x16x32_bf16 v[54:57], v[146:149], v[184:187], v[54:57]
	v_mfma_f32_16x16x32_bf16 v[50:53], v[170:173], v[184:187], v[50:53]
	v_mfma_f32_16x16x32_bf16 v[38:41], v[146:149], v[192:195], v[38:41]
	v_mfma_f32_16x16x32_bf16 v[34:37], v[170:173], v[192:195], v[34:37]
	v_mfma_f32_16x16x32_bf16 v[22:25], v[146:149], v[204:207], v[22:25]
	v_mfma_f32_16x16x32_bf16 v[18:21], v[170:173], v[204:207], v[18:21]
	v_mfma_f32_16x16x32_bf16 v[6:9], v[146:149], v[212:215], v[6:9]
	v_mfma_f32_16x16x32_bf16 v[2:5], v[170:173], v[212:215], v[2:5]
	v_mfma_f32_16x16x32_bf16 v[54:57], v[166:169], v[188:191], v[54:57]
	v_mfma_f32_16x16x32_bf16 v[50:53], v[174:177], v[188:191], v[50:53]
	v_mfma_f32_16x16x32_bf16 v[38:41], v[166:169], v[200:203], v[38:41]
	v_mfma_f32_16x16x32_bf16 v[34:37], v[174:177], v[200:203], v[34:37]
	v_mfma_f32_16x16x32_bf16 v[22:25], v[166:169], v[208:211], v[22:25]
	v_mfma_f32_16x16x32_bf16 v[18:21], v[174:177], v[208:211], v[18:21]
	v_mfma_f32_16x16x32_bf16 v[6:9], v[166:169], v[216:219], v[6:9]
	v_mfma_f32_16x16x32_bf16 v[2:5], v[174:177], v[216:219], v[2:5]
	s_setprio 0
	s_barrier
	s_add_i32 s56, s56, 2
	s_add_u32 s30, s30, 0x100
	s_addc_u32 s31, s31, 0
	s_add_u32 s52, s52, 0x100
	s_addc_u32 s53, s53, 0
	s_cmp_gt_u32 s56, 29
	s_cbranch_scc0 .LBB0_857
	s_and_b64 vcc, exec, s[10:11]
	s_cbranch_vccz .LBB0_860
	s_barrier

; #define PG8_STAGE(bufoff, gbase, voff) do { _Pragma("unroll") for (int _i = 0; _i < 2; ++_i) \
;         __builtin_amdgcn_global_load_lds((const unsigned*)((const char*)(gbase) + (voff)[_i]), (PG8_LAS unsigned*)(lds + (bufoff) + ldsw + _i * 8192), 16, 0, 0); } while (0)
; #define PG8_LDA(dst, b, h) do { _Pragma("unroll") for (int m = 0; m < 4; ++m) _Pragma("unroll") for (int k = 0; k < 2; ++k) dst[m][k] = *(const PG8_LAS bf16x8*)(lds + PG8_SA(b, h) + aoff + m * 2048 + k * 1024); } while (0)
; #define PG8_LDB(dst, b, h) do { _Pragma("unroll") for (int n = 0; n < 2; ++n) _Pragma("unroll") for (int k = 0; k < 2; ++k) dst[n][k] = *(const PG8_LAS bf16x8*)(lds + PG8_SB(b, h) + boff + n * 2048 + k * 1024); } while (0)
; #define PG8_MMA(ai, bj, At, Bt) do { __builtin_amdgcn_s_setprio(1); _Pragma("unroll") for (int m = 0; m < 4; ++m) _Pragma("unroll") for (int n = 0; n < 2; ++n) _Pragma("unroll") for (int k = 0; k < 2; ++k) \
;         acc[ai][bj][m][n] = __builtin_amdgcn_mfma_f32_16x16x32_bf16(Bt[n][k], At[m][k], acc[ai][bj][m][n], 0, 0, 0); __builtin_amdgcn_s_setprio(0); } while (0)
; #define PG8_WAIT_V(n) asm volatile("s_waitcnt vmcnt(" #n ")" ::: "memory")
; #define PG8_WAIT_L(n) asm volatile("s_waitcnt lgkmcnt(" #n ")" ::: "memory")
; #define PG8_BAR __builtin_amdgcn_s_barrier()
; #define PG8_SCHED __builtin_amdgcn_sched_barrier(0)
; template <class Epi, class Sched, bool ALIGN_EPI = false, bool SP2 = false>
; __device__ __forceinline__ void gemm_phase(PG8_LAS unsigned char* lds, const Gemm g, const Sched& S, const Epi& E) {
;     ...
;             PG8_LDB(B0, 0, 0); PG8_LDB(B1, 0, 1); PG8_SCHED; PG8_LDA(At, 0, 0); PG8_STAGE(PG8_SA(1, 1), a1 + hstep, voffA);
;             PG8_WAIT_V(8); PG8_WAIT_L(0); PG8_BAR; PG8_MMA(0, 0, At, B0); PG8_MMA(0, 1, At, B1); PG8_BAR; PG8_SCHED;
;             PG8_LDA(At, 0, 1); PG8_STAGE(PG8_SB(0, 0), b2, voffB); PG8_STAGE(PG8_SB(0, 1), b2 + hstep, voffB); PG8_STAGE(PG8_SA(0, 0), a2, voffA);
;             PG8_WAIT_V(8); PG8_WAIT_L(0); PG8_BAR; PG8_MMA(1, 0, At, B0); PG8_MMA(1, 1, At, B1); PG8_BAR; PG8_SCHED;
.LBB0_884:
	s_add_u32 s34, s30, 0xfff80000
	s_addc_u32 s35, s31, -1
	v_lshl_add_u64 v[208:209], s[34:35], 0, v[178:179]
	s_mov_b32 m0, s43
	s_nop 0
	global_load_lds_dwordx4 v[208:209], off
	v_lshl_add_u64 v[208:209], s[34:35], 0, v[182:183]
	s_mov_b32 m0, s44
	s_nop 0
	global_load_lds_dwordx4 v[208:209], off
	s_add_u32 s34, s34, 0x80
	s_addc_u32 s35, s35, 0
	ds_read_b128 v[130:133], v211
	ds_read_b128 v[134:137], v211 offset:1024
	ds_read_b128 v[138:141], v211 offset:2048
	ds_read_b128 v[142:145], v211 offset:3072
	ds_read_b128 v[146:149], v212
	ds_read_b128 v[150:153], v212 offset:1024
	ds_read_b128 v[154:157], v212 offset:2048
	ds_read_b128 v[158:161], v212 offset:3072
	s_cmp_eq_u32 s56, 28
	s_cselect_b32 s37, s15, s35
	s_cselect_b32 s36, s50, s34
	s_cselect_b32 s35, s13, s53
	s_cselect_b32 s34, s51, s52
	v_lshl_add_u64 v[208:209], s[30:31], 0, v[186:187]
	s_add_i32 m0, s29, 0xc000
	ds_read_b128 v[162:165], v213
	ds_read_b128 v[166:169], v213 offset:1024
	ds_read_b128 v[170:173], v213 offset:2048
	ds_read_b128 v[174:177], v213 offset:3072
	ds_read_b128 v[194:197], v213 offset:4096
	ds_read_b128 v[200:203], v213 offset:5120
	ds_read_b128 v[204:207], v213 offset:6144
	ds_read_b128 v[214:217], v213 offset:7168
	global_load_lds_dwordx4 v[208:209], off
	v_lshl_add_u64 v[208:209], s[30:31], 0, v[188:189]
	s_add_i32 m0, s29, 0xe000
	s_nop 0
	global_load_lds_dwordx4 v[208:209], off
	s_waitcnt vmcnt(8)
	s_waitcnt lgkmcnt(0)
	s_barrier
	s_setprio 1
	s_waitcnt lgkmcnt(0)
	v_mfma_f32_16x16x32_bf16 v[126:129], v[130:133], v[162:165], v[126:129]
	v_mfma_f32_16x16x32_bf16 v[122:125], v[138:141], v[162:165], v[122:125]
	v_mfma_f32_16x16x32_bf16 v[110:113], v[130:133], v[170:173], v[110:113]
	v_mfma_f32_16x16x32_bf16 v[106:109], v[138:141], v[170:173], v[106:109]
	v_mfma_f32_16x16x32_bf16 v[94:97], v[130:133], v[194:197], v[94:97]
	v_mfma_f32_16x16x32_bf16 v[90:93], v[138:141], v[194:197], v[90:93]
	v_mfma_f32_16x16x32_bf16 v[78:81], v[130:133], v[204:207], v[78:81]
	v_mfma_f32_16x16x32_bf16 v[74:77], v[138:141], v[204:207], v[74:77]
	v_mfma_f32_16x16x32_bf16 v[126:129], v[134:137], v[166:169], v[126:129]
	v_mfma_f32_16x16x32_bf16 v[122:125], v[142:145], v[166:169], v[122:125]
	v_mfma_f32_16x16x32_bf16 v[110:113], v[134:137], v[174:177], v[110:113]
	v_mfma_f32_16x16x32_bf16 v[106:109], v[142:145], v[174:177], v[106:109]
	v_mfma_f32_16x16x32_bf16 v[94:97], v[134:137], v[200:203], v[94:97]
	v_mfma_f32_16x16x32_bf16 v[90:93], v[142:145], v[200:203], v[90:93]
	v_mfma_f32_16x16x32_bf16 v[78:81], v[134:137], v[214:217], v[78:81]
	v_mfma_f32_16x16x32_bf16 v[74:77], v[142:145], v[214:217], v[74:77]
	s_setprio 0
	s_setprio 1
	v_mfma_f32_16x16x32_bf16 v[118:121], v[146:149], v[162:165], v[118:121]
	v_mfma_f32_16x16x32_bf16 v[114:117], v[154:157], v[162:165], v[114:117]
	v_mfma_f32_16x16x32_bf16 v[102:105], v[146:149], v[170:173], v[102:105]
	v_mfma_f32_16x16x32_bf16 v[98:101], v[154:157], v[170:173], v[98:101]
	v_mfma_f32_16x16x32_bf16 v[86:89], v[146:149], v[194:197], v[86:89]
	v_mfma_f32_16x16x32_bf16 v[82:85], v[154:157], v[194:197], v[82:85]
	v_mfma_f32_16x16x32_bf16 v[70:73], v[146:149], v[204:207], v[70:73]
	v_mfma_f32_16x16x32_bf16 v[66:69], v[154:157], v[204:207], v[66:69]
	v_mfma_f32_16x16x32_bf16 v[118:121], v[150:153], v[166:169], v[118:121]
	v_mfma_f32_16x16x32_bf16 v[114:117], v[158:161], v[166:169], v[114:117]
	v_mfma_f32_16x16x32_bf16 v[102:105], v[150:153], v[174:177], v[102:105]
	v_mfma_f32_16x16x32_bf16 v[98:101], v[158:161], v[174:177], v[98:101]
	v_mfma_f32_16x16x32_bf16 v[86:89], v[150:153], v[200:203], v[86:89]
	v_mfma_f32_16x16x32_bf16 v[82:85], v[158:161], v[200:203], v[82:85]
	v_mfma_f32_16x16x32_bf16 v[70:73], v[150:153], v[214:217], v[70:73]
	v_mfma_f32_16x16x32_bf16 v[66:69], v[158:161], v[214:217], v[66:69]
	s_setprio 0
	s_barrier
	s_add_i32 s57, s46, s38
	v_lshl_add_u64 v[208:209], s[34:35], 0, v[180:181]
	s_mov_b32 m0, s57
	ds_read_b128 v[162:165], v213 offset:16384
	ds_read_b128 v[166:169], v213 offset:17408
	ds_read_b128 v[170:173], v213 offset:18432
	ds_read_b128 v[174:177], v213 offset:19456
	ds_read_b128 v[194:197], v213 offset:20480
	ds_read_b128 v[200:203], v213 offset:21504
	ds_read_b128 v[204:207], v213 offset:22528
	ds_read_b128 v[214:217], v213 offset:23552
	global_load_lds_dwordx4 v[208:209], off
	s_add_i32 m0, s57, 0x2000
	s_add_u32 s58, s34, 0x80000
	v_lshl_add_u64 v[218:219], s[34:35], 0, v[184:185]
	s_addc_u32 s59, s35, 0
	s_add_i32 s57, s47, s38
	global_load_lds_dwordx4 v[218:219], off
	v_lshl_add_u64 v[220:221], s[58:59], 0, v[180:181]
	s_mov_b32 m0, s57
	v_lshl_add_u64 v[222:223], s[36:37], 0, v[182:183]
	global_load_lds_dwordx4 v[220:221], off
	v_lshl_add_u64 v[220:221], s[58:59], 0, v[184:185]
	s_add_i32 m0, s57, 0x2000
	s_nop 0
	global_load_lds_dwordx4 v[220:221], off
	v_lshl_add_u64 v[220:221], s[36:37], 0, v[178:179]
	s_waitcnt vmcnt(6)
	s_waitcnt lgkmcnt(0)
	s_barrier
; #define PG8_STAGE(bufoff, gbase, voff) do { _Pragma("unroll") for (int _i = 0; _i < 2; ++_i) \
;         __builtin_amdgcn_global_load_lds((const unsigned*)((const char*)(gbase) + (voff)[_i]), (PG8_LAS unsigned*)(lds + (bufoff) + ldsw + _i * 8192), 16, 0, 0); } while (0)
; #define PG8_LDA(dst, b, h) do { _Pragma("unroll") for (int m = 0; m < 4; ++m) _Pragma("unroll") for (int k = 0; k < 2; ++k) dst[m][k] = *(const PG8_LAS bf16x8*)(lds + PG8_SA(b, h) + aoff + m * 2048 + k * 1024); } while (0)
; #define PG8_LDB(dst, b, h) do { _Pragma("unroll") for (int n = 0; n < 2; ++n) _Pragma("unroll") for (int k = 0; k < 2; ++k) dst[n][k] = *(const PG8_LAS bf16x8*)(lds + PG8_SB(b, h) + boff + n * 2048 + k * 1024); } while (0)
; #define PG8_MMA(ai, bj, At, Bt) do { __builtin_amdgcn_s_setprio(1); _Pragma("unroll") for (int m = 0; m < 4; ++m) _Pragma("unroll") for (int n = 0; n < 2; ++n) _Pragma("unroll") for (int k = 0; k < 2; ++k) \
;         acc[ai][bj][m][n] = __builtin_amdgcn_mfma_f32_16x16x32_bf16(Bt[n][k], At[m][k], acc[ai][bj][m][n], 0, 0, 0); __builtin_amdgcn_s_setprio(0); } while (0)
; #define PG8_WAIT_V(n) asm volatile("s_waitcnt vmcnt(" #n ")" ::: "memory")
; #define PG8_WAIT_L(n) asm volatile("s_waitcnt lgkmcnt(" #n ")" ::: "memory")
; #define PG8_BAR __builtin_amdgcn_s_barrier()
; #define PG8_SCHED __builtin_amdgcn_sched_barrier(0)
; template <class Epi, class Sched, bool ALIGN_EPI = false, bool SP2 = false>
; __device__ __forceinline__ void gemm_phase(PG8_LAS unsigned char* lds, const Gemm g, const Sched& S, const Epi& E) {
;     ...
;             PG8_WAIT_V(8); PG8_WAIT_L(0); PG8_BAR; PG8_MMA(1, 0, At, B0); PG8_MMA(1, 1, At, B1); PG8_BAR; PG8_SCHED;
;             PG8_LDB(B0, 1, 0); PG8_LDB(B1, 1, 1); PG8_SCHED; PG8_LDA(At, 1, 0); PG8_STAGE(PG8_SA(0, 1), a2 + hstep, voffA);
	s_setprio 1
	s_waitcnt lgkmcnt(0)
	v_mfma_f32_16x16x32_bf16 v[62:65], v[130:133], v[162:165], v[62:65]
	v_mfma_f32_16x16x32_bf16 v[58:61], v[138:141], v[162:165], v[58:61]
	v_mfma_f32_16x16x32_bf16 v[46:49], v[130:133], v[170:173], v[46:49]
	v_mfma_f32_16x16x32_bf16 v[42:45], v[138:141], v[170:173], v[42:45]
	v_mfma_f32_16x16x32_bf16 v[30:33], v[130:133], v[194:197], v[30:33]
	v_mfma_f32_16x16x32_bf16 v[26:29], v[138:141], v[194:197], v[26:29]
	v_mfma_f32_16x16x32_bf16 v[14:17], v[130:133], v[204:207], v[14:17]
	v_mfma_f32_16x16x32_bf16 v[10:13], v[138:141], v[204:207], v[10:13]
	v_mfma_f32_16x16x32_bf16 v[62:65], v[134:137], v[166:169], v[62:65]
	v_mfma_f32_16x16x32_bf16 v[58:61], v[142:145], v[166:169], v[58:61]
	v_mfma_f32_16x16x32_bf16 v[46:49], v[134:137], v[174:177], v[46:49]
	v_mfma_f32_16x16x32_bf16 v[42:45], v[142:145], v[174:177], v[42:45]
	v_mfma_f32_16x16x32_bf16 v[30:33], v[134:137], v[200:203], v[30:33]
	v_mfma_f32_16x16x32_bf16 v[26:29], v[142:145], v[200:203], v[26:29]
	v_mfma_f32_16x16x32_bf16 v[14:17], v[134:137], v[214:217], v[14:17]
	v_mfma_f32_16x16x32_bf16 v[10:13], v[142:145], v[214:217], v[10:13]
	s_setprio 0
	s_setprio 1
	v_mfma_f32_16x16x32_bf16 v[54:57], v[146:149], v[162:165], v[54:57]
	v_mfma_f32_16x16x32_bf16 v[50:53], v[154:157], v[162:165], v[50:53]
	v_mfma_f32_16x16x32_bf16 v[38:41], v[146:149], v[170:173], v[38:41]
	v_mfma_f32_16x16x32_bf16 v[34:37], v[154:157], v[170:173], v[34:37]
	v_mfma_f32_16x16x32_bf16 v[22:25], v[146:149], v[194:197], v[22:25]
	v_mfma_f32_16x16x32_bf16 v[18:21], v[154:157], v[194:197], v[18:21]
	v_mfma_f32_16x16x32_bf16 v[6:9], v[146:149], v[204:207], v[6:9]
	v_mfma_f32_16x16x32_bf16 v[2:5], v[154:157], v[204:207], v[2:5]
	v_mfma_f32_16x16x32_bf16 v[54:57], v[150:153], v[166:169], v[54:57]
	v_mfma_f32_16x16x32_bf16 v[50:53], v[158:161], v[166:169], v[50:53]
	v_mfma_f32_16x16x32_bf16 v[38:41], v[150:153], v[174:177], v[38:41]
	v_mfma_f32_16x16x32_bf16 v[34:37], v[158:161], v[174:177], v[34:37]
	v_mfma_f32_16x16x32_bf16 v[22:25], v[150:153], v[200:203], v[22:25]
	v_mfma_f32_16x16x32_bf16 v[18:21], v[158:161], v[200:203], v[18:21]
	v_mfma_f32_16x16x32_bf16 v[6:9], v[150:153], v[214:217], v[6:9]
	v_mfma_f32_16x16x32_bf16 v[2:5], v[158:161], v[214:217], v[2:5]
	s_setprio 0
	s_barrier
	s_mov_b32 m0, s29
	s_nop 0
	global_load_lds_dwordx4 v[220:221], off
	s_mov_b32 m0, s39
	s_nop 0
	global_load_lds_dwordx4 v[222:223], off
	s_add_i32 s57, 0, 0x18000
	s_add_i32 s58, 0, 0x1c000
	v_add_u32_e32 v142, s57, v199
	v_add_u32_e32 v158, s58, v199
	ds_read_b128 v[130:133], v142
	ds_read_b128 v[134:137], v142 offset:1024
	ds_read_b128 v[138:141], v142 offset:2048
	ds_read_b128 v[142:145], v142 offset:3072
	ds_read_b128 v[146:149], v158
	ds_read_b128 v[150:153], v158 offset:1024
	ds_read_b128 v[154:157], v158 offset:2048
	ds_read_b128 v[158:161], v158 offset:3072
	s_add_u32 s36, s36, 0x80000
	s_addc_u32 s37, s37, 0
	s_mov_b32 m0, s40
	v_lshl_add_u64 v[224:225], s[36:37], 0, v[178:179]
	ds_read_b128 v[162:165], v213 offset:32768
	ds_read_b128 v[166:169], v213 offset:33792
	ds_read_b128 v[170:173], v213 offset:34816
	ds_read_b128 v[174:177], v213 offset:35840
	ds_read_b128 v[194:197], v213 offset:36864
	ds_read_b128 v[200:203], v213 offset:37888
	ds_read_b128 v[204:207], v213 offset:38912
	ds_read_b128 v[214:217], v213 offset:39936
	global_load_lds_dwordx4 v[224:225], off
	v_lshl_add_u64 v[224:225], s[36:37], 0, v[182:183]
	s_mov_b32 m0, s41
	s_nop 0
	global_load_lds_dwordx4 v[224:225], off
	s_waitcnt vmcnt(8)
	s_waitcnt lgkmcnt(0)
	s_barrier
; #define PG8_STAGE(bufoff, gbase, voff) do { _Pragma("unroll") for (int _i = 0; _i < 2; ++_i) \
;         __builtin_amdgcn_global_load_lds((const unsigned*)((const char*)(gbase) + (voff)[_i]), (PG8_LAS unsigned*)(lds + (bufoff) + ldsw + _i * 8192), 16, 0, 0); } while (0)
; #define PG8_LDA(dst, b, h) do { _Pragma("unroll") for (int m = 0; m < 4; ++m) _Pragma("unroll") for (int k = 0; k < 2; ++k) dst[m][k] = *(const PG8_LAS bf16x8*)(lds + PG8_SA(b, h) + aoff + m * 2048 + k * 1024); } while (0)
; #define PG8_MMA(ai, bj, At, Bt) do { __builtin_amdgcn_s_setprio(1); _Pragma("unroll") for (int m = 0; m < 4; ++m) _Pragma("unroll") for (int n = 0; n < 2; ++n) _Pragma("unroll") for (int k = 0; k < 2; ++k) \
;         acc[ai][bj][m][n] = __builtin_amdgcn_mfma_f32_16x16x32_bf16(Bt[n][k], At[m][k], acc[ai][bj][m][n], 0, 0, 0); __builtin_amdgcn_s_setprio(0); } while (0)
; #define PG8_WAIT_V(n) asm volatile("s_waitcnt vmcnt(" #n ")" ::: "memory")
; #define PG8_WAIT_L(n) asm volatile("s_waitcnt lgkmcnt(" #n ")" ::: "memory")
; #define PG8_BAR __builtin_amdgcn_s_barrier()
; #define PG8_SCHED __builtin_amdgcn_sched_barrier(0)
; template <class Epi, class Sched, bool ALIGN_EPI = false, bool SP2 = false>
; __device__ __forceinline__ void gemm_phase(PG8_LAS unsigned char* lds, const Gemm g, const Sched& S, const Epi& E) {
;     ...
;         for (int t = 0; t < nt; t += 2) {
;             const bool last = (t == nt - 2);
;             const char* a1 = cA + (size_t)(t + 1) * kstep;
;             const char* a2 = last ? nA : cA + (size_t)(t + 2) * kstep; const char* b2 = last ? nB : cB + (size_t)(t + 2) * kstep;
;     ...
;             PG8_WAIT_V(8); PG8_WAIT_L(0); PG8_BAR; PG8_MMA(0, 0, At, B0); PG8_MMA(0, 1, At, B1); PG8_BAR; PG8_SCHED;
;             PG8_LDA(At, 1, 1); PG8_STAGE(PG8_SB(1, 0), b3, voffB); PG8_STAGE(PG8_SB(1, 1), b3 + hstep, voffB); PG8_STAGE(PG8_SA(1, 0), a3, voffA);
;             PG8_WAIT_V(8); PG8_WAIT_L(0); PG8_BAR; PG8_MMA(1, 0, At, B0); PG8_MMA(1, 1, At, B1); PG8_BAR; PG8_SCHED;
	s_setprio 1
	s_waitcnt lgkmcnt(0)
	v_mfma_f32_16x16x32_bf16 v[126:129], v[130:133], v[162:165], v[126:129]
	v_mfma_f32_16x16x32_bf16 v[122:125], v[138:141], v[162:165], v[122:125]
	v_mfma_f32_16x16x32_bf16 v[110:113], v[130:133], v[170:173], v[110:113]
	v_mfma_f32_16x16x32_bf16 v[106:109], v[138:141], v[170:173], v[106:109]
	v_mfma_f32_16x16x32_bf16 v[94:97], v[130:133], v[194:197], v[94:97]
	v_mfma_f32_16x16x32_bf16 v[90:93], v[138:141], v[194:197], v[90:93]
	v_mfma_f32_16x16x32_bf16 v[78:81], v[130:133], v[204:207], v[78:81]
	v_mfma_f32_16x16x32_bf16 v[74:77], v[138:141], v[204:207], v[74:77]
	v_mfma_f32_16x16x32_bf16 v[126:129], v[134:137], v[166:169], v[126:129]
	v_mfma_f32_16x16x32_bf16 v[122:125], v[142:145], v[166:169], v[122:125]
	v_mfma_f32_16x16x32_bf16 v[110:113], v[134:137], v[174:177], v[110:113]
	v_mfma_f32_16x16x32_bf16 v[106:109], v[142:145], v[174:177], v[106:109]
	v_mfma_f32_16x16x32_bf16 v[94:97], v[134:137], v[200:203], v[94:97]
	v_mfma_f32_16x16x32_bf16 v[90:93], v[142:145], v[200:203], v[90:93]
	v_mfma_f32_16x16x32_bf16 v[78:81], v[134:137], v[214:217], v[78:81]
	v_mfma_f32_16x16x32_bf16 v[74:77], v[142:145], v[214:217], v[74:77]
	s_setprio 0
	s_setprio 1
	v_mfma_f32_16x16x32_bf16 v[118:121], v[146:149], v[162:165], v[118:121]
	v_mfma_f32_16x16x32_bf16 v[114:117], v[154:157], v[162:165], v[114:117]
	v_mfma_f32_16x16x32_bf16 v[102:105], v[146:149], v[170:173], v[102:105]
	v_mfma_f32_16x16x32_bf16 v[98:101], v[154:157], v[170:173], v[98:101]
	v_mfma_f32_16x16x32_bf16 v[86:89], v[146:149], v[194:197], v[86:89]
	v_mfma_f32_16x16x32_bf16 v[82:85], v[154:157], v[194:197], v[82:85]
	v_mfma_f32_16x16x32_bf16 v[70:73], v[146:149], v[204:207], v[70:73]
	v_mfma_f32_16x16x32_bf16 v[66:69], v[154:157], v[204:207], v[66:69]
	v_mfma_f32_16x16x32_bf16 v[118:121], v[150:153], v[166:169], v[118:121]
	v_mfma_f32_16x16x32_bf16 v[114:117], v[158:161], v[166:169], v[114:117]
	v_mfma_f32_16x16x32_bf16 v[102:105], v[150:153], v[174:177], v[102:105]
	v_mfma_f32_16x16x32_bf16 v[98:101], v[158:161], v[174:177], v[98:101]
	v_mfma_f32_16x16x32_bf16 v[86:89], v[150:153], v[200:203], v[86:89]
	v_mfma_f32_16x16x32_bf16 v[82:85], v[158:161], v[200:203], v[82:85]
	v_mfma_f32_16x16x32_bf16 v[70:73], v[150:153], v[214:217], v[70:73]
	v_mfma_f32_16x16x32_bf16 v[66:69], v[158:161], v[214:217], v[66:69]
	s_setprio 0
	s_barrier
	s_add_i32 s36, s57, s38
	v_lshl_add_u64 v[208:209], v[208:209], 0, s[8:9]
	s_mov_b32 m0, s36
	ds_read_b128 v[162:165], v213 offset:49152
	ds_read_b128 v[166:169], v213 offset:50176
	ds_read_b128 v[170:173], v213 offset:51200
	ds_read_b128 v[174:177], v213 offset:52224
	ds_read_b128 v[194:197], v213 offset:53248
	ds_read_b128 v[200:203], v213 offset:54272
	ds_read_b128 v[204:207], v213 offset:55296
	ds_read_b128 v[214:217], v213 offset:56320
	global_load_lds_dwordx4 v[208:209], off
	s_add_i32 m0, s36, 0x2000
	s_add_u32 s34, s34, 0x80080
	v_lshl_add_u64 v[208:209], v[218:219], 0, s[8:9]
	s_addc_u32 s35, s35, 0
	s_add_i32 s36, s58, s38
	global_load_lds_dwordx4 v[208:209], off
	v_lshl_add_u64 v[208:209], s[34:35], 0, v[180:181]
	s_mov_b32 m0, s36
	s_nop 0
	global_load_lds_dwordx4 v[208:209], off
	v_lshl_add_u64 v[208:209], s[34:35], 0, v[184:185]
	s_add_i32 m0, s36, 0x2000
	s_nop 0
	global_load_lds_dwordx4 v[208:209], off
	s_waitcnt vmcnt(6)
	s_waitcnt lgkmcnt(0)
	s_barrier
	s_setprio 1
	s_waitcnt lgkmcnt(0)
	v_mfma_f32_16x16x32_bf16 v[62:65], v[130:133], v[162:165], v[62:65]
	v_mfma_f32_16x16x32_bf16 v[58:61], v[138:141], v[162:165], v[58:61]
	v_mfma_f32_16x16x32_bf16 v[46:49], v[130:133], v[170:173], v[46:49]
	v_mfma_f32_16x16x32_bf16 v[42:45], v[138:141], v[170:173], v[42:45]
	v_mfma_f32_16x16x32_bf16 v[30:33], v[130:133], v[194:197], v[30:33]
	v_mfma_f32_16x16x32_bf16 v[26:29], v[138:141], v[194:197], v[26:29]
	v_mfma_f32_16x16x32_bf16 v[14:17], v[130:133], v[204:207], v[14:17]
	v_mfma_f32_16x16x32_bf16 v[10:13], v[138:141], v[204:207], v[10:13]
	v_mfma_f32_16x16x32_bf16 v[62:65], v[134:137], v[166:169], v[62:65]
	v_mfma_f32_16x16x32_bf16 v[58:61], v[142:145], v[166:169], v[58:61]
	v_mfma_f32_16x16x32_bf16 v[46:49], v[134:137], v[174:177], v[46:49]
	v_mfma_f32_16x16x32_bf16 v[42:45], v[142:145], v[174:177], v[42:45]
	v_mfma_f32_16x16x32_bf16 v[30:33], v[134:137], v[200:203], v[30:33]
	v_mfma_f32_16x16x32_bf16 v[26:29], v[142:145], v[200:203], v[26:29]
	v_mfma_f32_16x16x32_bf16 v[14:17], v[134:137], v[214:217], v[14:17]
	v_mfma_f32_16x16x32_bf16 v[10:13], v[142:145], v[214:217], v[10:13]
	s_setprio 0
	s_setprio 1
	v_mfma_f32_16x16x32_bf16 v[54:57], v[146:149], v[162:165], v[54:57]
	v_mfma_f32_16x16x32_bf16 v[50:53], v[154:157], v[162:165], v[50:53]
	v_mfma_f32_16x16x32_bf16 v[38:41], v[146:149], v[170:173], v[38:41]
	v_mfma_f32_16x16x32_bf16 v[34:37], v[154:157], v[170:173], v[34:37]
	v_mfma_f32_16x16x32_bf16 v[22:25], v[146:149], v[194:197], v[22:25]
	v_mfma_f32_16x16x32_bf16 v[18:21], v[154:157], v[194:197], v[18:21]
	v_mfma_f32_16x16x32_bf16 v[6:9], v[146:149], v[204:207], v[6:9]
	v_mfma_f32_16x16x32_bf16 v[2:5], v[154:157], v[204:207], v[2:5]
	v_mfma_f32_16x16x32_bf16 v[54:57], v[150:153], v[166:169], v[54:57]
	v_mfma_f32_16x16x32_bf16 v[50:53], v[158:161], v[166:169], v[50:53]
	v_mfma_f32_16x16x32_bf16 v[38:41], v[150:153], v[174:177], v[38:41]
	v_mfma_f32_16x16x32_bf16 v[34:37], v[158:161], v[174:177], v[34:37]
	v_mfma_f32_16x16x32_bf16 v[22:25], v[150:153], v[200:203], v[22:25]
	v_mfma_f32_16x16x32_bf16 v[18:21], v[158:161], v[200:203], v[18:21]
	v_mfma_f32_16x16x32_bf16 v[6:9], v[150:153], v[214:217], v[6:9]
	v_mfma_f32_16x16x32_bf16 v[2:5], v[158:161], v[214:217], v[2:5]
	s_setprio 0
	s_barrier
	s_add_i32 s56, s56, 2
	s_add_u32 s30, s30, 0x100
	s_addc_u32 s31, s31, 0
	s_add_u32 s52, s52, 0x100
	s_addc_u32 s53, s53, 0
	s_cmp_gt_u32 s56, 29
	s_cbranch_scc0 .LBB0_884
	s_and_b64 vcc, exec, s[10:11]
	s_cbranch_vccz .LBB0_887
	s_barrier

; #define PG8_STAGE(bufoff, gbase, voff) do { _Pragma("unroll") for (int _i = 0; _i < 2; ++_i) \
;         __builtin_amdgcn_global_load_lds((const unsigned*)((const char*)(gbase) + (voff)[_i]), (PG8_LAS unsigned*)(lds + (bufoff) + ldsw + _i * 8192), 16, 0, 0); } while (0)
; #define PG8_LDA(dst, b, h) do { _Pragma("unroll") for (int m = 0; m < 4; ++m) _Pragma("unroll") for (int k = 0; k < 2; ++k) dst[m][k] = *(const PG8_LAS bf16x8*)(lds + PG8_SA(b, h) + aoff + m * 2048 + k * 1024); } while (0)
; #define PG8_LDB(dst, b, h) do { _Pragma("unroll") for (int n = 0; n < 2; ++n) _Pragma("unroll") for (int k = 0; k < 2; ++k) dst[n][k] = *(const PG8_LAS bf16x8*)(lds + PG8_SB(b, h) + boff + n * 2048 + k * 1024); } while (0)
; #define PG8_MMA(ai, bj, At, Bt) do { __builtin_amdgcn_s_setprio(1); _Pragma("unroll") for (int m = 0; m < 4; ++m) _Pragma("unroll") for (int n = 0; n < 2; ++n) _Pragma("unroll") for (int k = 0; k < 2; ++k) \
;         acc[ai][bj][m][n] = __builtin_amdgcn_mfma_f32_16x16x32_bf16(Bt[n][k], At[m][k], acc[ai][bj][m][n], 0, 0, 0); __builtin_amdgcn_s_setprio(0); } while (0)
; #define PG8_WAIT_V(n) asm volatile("s_waitcnt vmcnt(" #n ")" ::: "memory")
; #define PG8_WAIT_L(n) asm volatile("s_waitcnt lgkmcnt(" #n ")" ::: "memory")
; #define PG8_BAR __builtin_amdgcn_s_barrier()
; #define PG8_SCHED __builtin_amdgcn_sched_barrier(0)
; template <class Epi, class Sched, bool ALIGN_EPI = false, bool SP2 = false>
; __device__ __forceinline__ void gemm_phase(PG8_LAS unsigned char* lds, const Gemm g, const Sched& S, const Epi& E) {
;     ...
;             PG8_LDB(B0, 0, 0); PG8_LDB(B1, 0, 1); PG8_SCHED; PG8_LDA(At, 0, 0); PG8_STAGE(PG8_SA(1, 1), a1 + hstep, voffA);
;             PG8_WAIT_V(8); PG8_WAIT_L(0); PG8_BAR; PG8_MMA(0, 0, At, B0); PG8_MMA(0, 1, At, B1); PG8_BAR; PG8_SCHED;
;             PG8_LDA(At, 0, 1); PG8_STAGE(PG8_SB(0, 0), b2, voffB); PG8_STAGE(PG8_SB(0, 1), b2 + hstep, voffB); PG8_STAGE(PG8_SA(0, 0), a2, voffA);
;             PG8_WAIT_V(8); PG8_WAIT_L(0); PG8_BAR; PG8_MMA(1, 0, At, B0); PG8_MMA(1, 1, At, B1); PG8_BAR; PG8_SCHED;
.LBB0_959:
	s_add_u32 s30, s28, 0xfff00000
	s_addc_u32 s31, s29, -1
	v_lshl_add_u64 v[196:197], s[30:31], 0, v[138:139]
	s_mov_b32 m0, s41
	s_nop 0
	global_load_lds_dwordx4 v[196:197], off
	v_lshl_add_u64 v[196:197], s[30:31], 0, v[142:143]
	s_mov_b32 m0, s42
	s_nop 0
	global_load_lds_dwordx4 v[196:197], off
	s_add_u32 s30, s30, 0x80
	s_addc_u32 s31, s31, 0
	ds_read_b128 v[130:133], v164
	ds_read_b128 v[134:137], v164 offset:1024
	ds_read_b128 v[154:157], v164 offset:2048
	ds_read_b128 v[158:161], v164 offset:3072
	ds_read_b128 v[168:171], v165
	ds_read_b128 v[172:175], v165 offset:1024
	ds_read_b128 v[176:179], v165 offset:2048
	ds_read_b128 v[180:183], v165 offset:3072
	s_cmp_eq_u32 s51, 60
	s_cselect_b32 s35, s13, s31
	s_cselect_b32 s34, s47, s30
	s_cselect_b32 s31, s11, s50
	s_cselect_b32 s30, s48, s49
	v_lshl_add_u64 v[196:197], s[28:29], 0, v[146:147]
	s_add_i32 m0, s27, 0xc000
	ds_read_b128 v[184:187], v166
	ds_read_b128 v[188:191], v166 offset:1024
	ds_read_b128 v[192:195], v166 offset:2048
	ds_read_b128 v[200:203], v166 offset:3072
	ds_read_b128 v[204:207], v166 offset:4096
	ds_read_b128 v[208:211], v166 offset:5120
	ds_read_b128 v[212:215], v166 offset:6144
	ds_read_b128 v[216:219], v166 offset:7168
	global_load_lds_dwordx4 v[196:197], off
	v_lshl_add_u64 v[196:197], s[28:29], 0, v[148:149]
	s_add_i32 m0, s27, 0xe000
	s_nop 0
	global_load_lds_dwordx4 v[196:197], off
	s_waitcnt vmcnt(8)
	s_waitcnt lgkmcnt(0)
	s_barrier
	s_setprio 1
	s_waitcnt lgkmcnt(0)
	v_mfma_f32_16x16x32_bf16 v[126:129], v[130:133], v[184:187], v[126:129]
	v_mfma_f32_16x16x32_bf16 v[122:125], v[154:157], v[184:187], v[122:125]
	v_mfma_f32_16x16x32_bf16 v[118:121], v[130:133], v[192:195], v[118:121]
	v_mfma_f32_16x16x32_bf16 v[114:117], v[154:157], v[192:195], v[114:117]
	v_mfma_f32_16x16x32_bf16 v[110:113], v[130:133], v[204:207], v[110:113]
	v_mfma_f32_16x16x32_bf16 v[102:105], v[154:157], v[204:207], v[102:105]
	v_mfma_f32_16x16x32_bf16 v[82:85], v[130:133], v[212:215], v[82:85]
	v_mfma_f32_16x16x32_bf16 v[74:77], v[154:157], v[212:215], v[74:77]
	v_mfma_f32_16x16x32_bf16 v[126:129], v[134:137], v[188:191], v[126:129]
	v_mfma_f32_16x16x32_bf16 v[122:125], v[158:161], v[188:191], v[122:125]
	v_mfma_f32_16x16x32_bf16 v[118:121], v[134:137], v[200:203], v[118:121]
	v_mfma_f32_16x16x32_bf16 v[114:117], v[158:161], v[200:203], v[114:117]
	v_mfma_f32_16x16x32_bf16 v[110:113], v[134:137], v[208:211], v[110:113]
	v_mfma_f32_16x16x32_bf16 v[102:105], v[158:161], v[208:211], v[102:105]
	v_mfma_f32_16x16x32_bf16 v[82:85], v[134:137], v[216:219], v[82:85]
	v_mfma_f32_16x16x32_bf16 v[74:77], v[158:161], v[216:219], v[74:77]
	s_setprio 0
	s_setprio 1
	v_mfma_f32_16x16x32_bf16 v[106:109], v[168:171], v[184:187], v[106:109]
	v_mfma_f32_16x16x32_bf16 v[98:101], v[176:179], v[184:187], v[98:101]
	v_mfma_f32_16x16x32_bf16 v[94:97], v[168:171], v[192:195], v[94:97]
	v_mfma_f32_16x16x32_bf16 v[90:93], v[176:179], v[192:195], v[90:93]
	v_mfma_f32_16x16x32_bf16 v[86:89], v[168:171], v[204:207], v[86:89]
	v_mfma_f32_16x16x32_bf16 v[78:81], v[176:179], v[204:207], v[78:81]
	v_mfma_f32_16x16x32_bf16 v[70:73], v[168:171], v[212:215], v[70:73]
	v_mfma_f32_16x16x32_bf16 v[66:69], v[176:179], v[212:215], v[66:69]
	v_mfma_f32_16x16x32_bf16 v[106:109], v[172:175], v[188:191], v[106:109]
	v_mfma_f32_16x16x32_bf16 v[98:101], v[180:183], v[188:191], v[98:101]
	v_mfma_f32_16x16x32_bf16 v[94:97], v[172:175], v[200:203], v[94:97]
	v_mfma_f32_16x16x32_bf16 v[90:93], v[180:183], v[200:203], v[90:93]
	v_mfma_f32_16x16x32_bf16 v[86:89], v[172:175], v[208:211], v[86:89]
	v_mfma_f32_16x16x32_bf16 v[78:81], v[180:183], v[208:211], v[78:81]
	v_mfma_f32_16x16x32_bf16 v[70:73], v[172:175], v[216:219], v[70:73]
	v_mfma_f32_16x16x32_bf16 v[66:69], v[180:183], v[216:219], v[66:69]
	s_setprio 0
	s_barrier
	s_add_i32 s52, s44, s36
	v_lshl_add_u64 v[196:197], s[30:31], 0, v[140:141]
	s_mov_b32 m0, s52
	ds_read_b128 v[184:187], v166 offset:16384
	ds_read_b128 v[188:191], v166 offset:17408
	ds_read_b128 v[192:195], v166 offset:18432
	ds_read_b128 v[200:203], v166 offset:19456
	ds_read_b128 v[204:207], v166 offset:20480
	ds_read_b128 v[208:211], v166 offset:21504
	ds_read_b128 v[212:215], v166 offset:22528
	ds_read_b128 v[216:219], v166 offset:23552
	global_load_lds_dwordx4 v[196:197], off
	s_add_i32 m0, s52, 0x2000
	s_add_u32 s52, s30, 0x100000
	v_lshl_add_u64 v[220:221], s[30:31], 0, v[144:145]
	s_addc_u32 s53, s31, 0
	s_add_i32 s54, s45, s36
	global_load_lds_dwordx4 v[220:221], off
	v_lshl_add_u64 v[222:223], s[52:53], 0, v[140:141]
	s_mov_b32 m0, s54
	v_lshl_add_u64 v[224:225], s[34:35], 0, v[142:143]
	global_load_lds_dwordx4 v[222:223], off
	v_lshl_add_u64 v[222:223], s[52:53], 0, v[144:145]
	s_add_i32 m0, s54, 0x2000
	s_nop 0
	global_load_lds_dwordx4 v[222:223], off
	v_lshl_add_u64 v[222:223], s[34:35], 0, v[138:139]
	s_waitcnt vmcnt(6)
	s_waitcnt lgkmcnt(0)
	s_barrier
; #define PG8_STAGE(bufoff, gbase, voff) do { _Pragma("unroll") for (int _i = 0; _i < 2; ++_i) \
;         __builtin_amdgcn_global_load_lds((const unsigned*)((const char*)(gbase) + (voff)[_i]), (PG8_LAS unsigned*)(lds + (bufoff) + ldsw + _i * 8192), 16, 0, 0); } while (0)
; #define PG8_LDA(dst, b, h) do { _Pragma("unroll") for (int m = 0; m < 4; ++m) _Pragma("unroll") for (int k = 0; k < 2; ++k) dst[m][k] = *(const PG8_LAS bf16x8*)(lds + PG8_SA(b, h) + aoff + m * 2048 + k * 1024); } while (0)
; #define PG8_LDB(dst, b, h) do { _Pragma("unroll") for (int n = 0; n < 2; ++n) _Pragma("unroll") for (int k = 0; k < 2; ++k) dst[n][k] = *(const PG8_LAS bf16x8*)(lds + PG8_SB(b, h) + boff + n * 2048 + k * 1024); } while (0)
; #define PG8_MMA(ai, bj, At, Bt) do { __builtin_amdgcn_s_setprio(1); _Pragma("unroll") for (int m = 0; m < 4; ++m) _Pragma("unroll") for (int n = 0; n < 2; ++n) _Pragma("unroll") for (int k = 0; k < 2; ++k) \
;         acc[ai][bj][m][n] = __builtin_amdgcn_mfma_f32_16x16x32_bf16(Bt[n][k], At[m][k], acc[ai][bj][m][n], 0, 0, 0); __builtin_amdgcn_s_setprio(0); } while (0)
; #define PG8_WAIT_V(n) asm volatile("s_waitcnt vmcnt(" #n ")" ::: "memory")
; #define PG8_WAIT_L(n) asm volatile("s_waitcnt lgkmcnt(" #n ")" ::: "memory")
; #define PG8_BAR __builtin_amdgcn_s_barrier()
; #define PG8_SCHED __builtin_amdgcn_sched_barrier(0)
; template <class Epi, class Sched, bool ALIGN_EPI = false, bool SP2 = false>
; __device__ __forceinline__ void gemm_phase(PG8_LAS unsigned char* lds, const Gemm g, const Sched& S, const Epi& E) {
;     ...
;             PG8_WAIT_V(8); PG8_WAIT_L(0); PG8_BAR; PG8_MMA(1, 0, At, B0); PG8_MMA(1, 1, At, B1); PG8_BAR; PG8_SCHED;
;             PG8_LDB(B0, 1, 0); PG8_LDB(B1, 1, 1); PG8_SCHED; PG8_LDA(At, 1, 0); PG8_STAGE(PG8_SA(0, 1), a2 + hstep, voffA);
	s_setprio 1
	s_waitcnt lgkmcnt(0)
	v_mfma_f32_16x16x32_bf16 v[62:65], v[130:133], v[184:187], v[62:65]
	v_mfma_f32_16x16x32_bf16 v[58:61], v[154:157], v[184:187], v[58:61]
	v_mfma_f32_16x16x32_bf16 v[50:53], v[130:133], v[192:195], v[50:53]
	v_mfma_f32_16x16x32_bf16 v[42:45], v[154:157], v[192:195], v[42:45]
	v_mfma_f32_16x16x32_bf16 v[34:37], v[130:133], v[204:207], v[34:37]
	v_mfma_f32_16x16x32_bf16 v[26:29], v[154:157], v[204:207], v[26:29]
	v_mfma_f32_16x16x32_bf16 v[18:21], v[130:133], v[212:215], v[18:21]
	v_mfma_f32_16x16x32_bf16 v[10:13], v[154:157], v[212:215], v[10:13]
	v_mfma_f32_16x16x32_bf16 v[62:65], v[134:137], v[188:191], v[62:65]
	v_mfma_f32_16x16x32_bf16 v[58:61], v[158:161], v[188:191], v[58:61]
	v_mfma_f32_16x16x32_bf16 v[50:53], v[134:137], v[200:203], v[50:53]
	v_mfma_f32_16x16x32_bf16 v[42:45], v[158:161], v[200:203], v[42:45]
	v_mfma_f32_16x16x32_bf16 v[34:37], v[134:137], v[208:211], v[34:37]
	v_mfma_f32_16x16x32_bf16 v[26:29], v[158:161], v[208:211], v[26:29]
	v_mfma_f32_16x16x32_bf16 v[18:21], v[134:137], v[216:219], v[18:21]
	v_mfma_f32_16x16x32_bf16 v[10:13], v[158:161], v[216:219], v[10:13]
	s_setprio 0
	s_setprio 1
	v_mfma_f32_16x16x32_bf16 v[54:57], v[168:171], v[184:187], v[54:57]
	v_mfma_f32_16x16x32_bf16 v[46:49], v[176:179], v[184:187], v[46:49]
	v_mfma_f32_16x16x32_bf16 v[38:41], v[168:171], v[192:195], v[38:41]
	v_mfma_f32_16x16x32_bf16 v[30:33], v[176:179], v[192:195], v[30:33]
	v_mfma_f32_16x16x32_bf16 v[22:25], v[168:171], v[204:207], v[22:25]
	v_mfma_f32_16x16x32_bf16 v[14:17], v[176:179], v[204:207], v[14:17]
	v_mfma_f32_16x16x32_bf16 v[6:9], v[168:171], v[212:215], v[6:9]
	v_mfma_f32_16x16x32_bf16 v[2:5], v[176:179], v[212:215], v[2:5]
	v_mfma_f32_16x16x32_bf16 v[54:57], v[172:175], v[188:191], v[54:57]
	v_mfma_f32_16x16x32_bf16 v[46:49], v[180:183], v[188:191], v[46:49]
	v_mfma_f32_16x16x32_bf16 v[38:41], v[172:175], v[200:203], v[38:41]
	v_mfma_f32_16x16x32_bf16 v[30:33], v[180:183], v[200:203], v[30:33]
	v_mfma_f32_16x16x32_bf16 v[22:25], v[172:175], v[208:211], v[22:25]
	v_mfma_f32_16x16x32_bf16 v[14:17], v[180:183], v[208:211], v[14:17]
	v_mfma_f32_16x16x32_bf16 v[6:9], v[172:175], v[216:219], v[6:9]
	v_mfma_f32_16x16x32_bf16 v[2:5], v[180:183], v[216:219], v[2:5]
	s_setprio 0
	s_barrier
	s_mov_b32 m0, s27
	s_nop 0
	global_load_lds_dwordx4 v[222:223], off
	s_mov_b32 m0, s37
	s_nop 0
	global_load_lds_dwordx4 v[224:225], off
	s_add_i32 s52, 0, 0x18000
	s_add_i32 s53, 0, 0x1c000
	v_add_u32_e32 v158, s52, v162
	v_add_u32_e32 v167, s53, v162
	ds_read_b128 v[130:133], v158
	ds_read_b128 v[134:137], v158 offset:1024
	ds_read_b128 v[154:157], v158 offset:2048
	ds_read_b128 v[158:161], v158 offset:3072
	ds_read_b128 v[168:171], v167
	ds_read_b128 v[172:175], v167 offset:1024
	ds_read_b128 v[176:179], v167 offset:2048
	ds_read_b128 v[180:183], v167 offset:3072
	s_add_u32 s34, s34, 0x100000
	s_addc_u32 s35, s35, 0
	s_mov_b32 m0, s38
	v_lshl_add_u64 v[226:227], s[34:35], 0, v[138:139]
	ds_read_b128 v[184:187], v166 offset:32768
	ds_read_b128 v[188:191], v166 offset:33792
	ds_read_b128 v[192:195], v166 offset:34816
	ds_read_b128 v[200:203], v166 offset:35840
	ds_read_b128 v[204:207], v166 offset:36864
	ds_read_b128 v[208:211], v166 offset:37888
	ds_read_b128 v[212:215], v166 offset:38912
	ds_read_b128 v[216:219], v166 offset:39936
	global_load_lds_dwordx4 v[226:227], off
	v_lshl_add_u64 v[226:227], s[34:35], 0, v[142:143]
	s_mov_b32 m0, s39
	s_nop 0
	global_load_lds_dwordx4 v[226:227], off
	s_waitcnt vmcnt(8)
	s_waitcnt lgkmcnt(0)
	s_barrier
; #define PG8_STAGE(bufoff, gbase, voff) do { _Pragma("unroll") for (int _i = 0; _i < 2; ++_i) \
;         __builtin_amdgcn_global_load_lds((const unsigned*)((const char*)(gbase) + (voff)[_i]), (PG8_LAS unsigned*)(lds + (bufoff) + ldsw + _i * 8192), 16, 0, 0); } while (0)
; #define PG8_LDA(dst, b, h) do { _Pragma("unroll") for (int m = 0; m < 4; ++m) _Pragma("unroll") for (int k = 0; k < 2; ++k) dst[m][k] = *(const PG8_LAS bf16x8*)(lds + PG8_SA(b, h) + aoff + m * 2048 + k * 1024); } while (0)
; #define PG8_MMA(ai, bj, At, Bt) do { __builtin_amdgcn_s_setprio(1); _Pragma("unroll") for (int m = 0; m < 4; ++m) _Pragma("unroll") for (int n = 0; n < 2; ++n) _Pragma("unroll") for (int k = 0; k < 2; ++k) \
;         acc[ai][bj][m][n] = __builtin_amdgcn_mfma_f32_16x16x32_bf16(Bt[n][k], At[m][k], acc[ai][bj][m][n], 0, 0, 0); __builtin_amdgcn_s_setprio(0); } while (0)
; #define PG8_WAIT_V(n) asm volatile("s_waitcnt vmcnt(" #n ")" ::: "memory")
; #define PG8_WAIT_L(n) asm volatile("s_waitcnt lgkmcnt(" #n ")" ::: "memory")
; #define PG8_BAR __builtin_amdgcn_s_barrier()
; #define PG8_SCHED __builtin_amdgcn_sched_barrier(0)
; template <class Epi, class Sched, bool ALIGN_EPI = false, bool SP2 = false>
; __device__ __forceinline__ void gemm_phase(PG8_LAS unsigned char* lds, const Gemm g, const Sched& S, const Epi& E) {
;     ...
;         for (int t = 0; t < nt; t += 2) {
;             const bool last = (t == nt - 2);
;             const char* a1 = cA + (size_t)(t + 1) * kstep;
;             const char* a2 = last ? nA : cA + (size_t)(t + 2) * kstep; const char* b2 = last ? nB : cB + (size_t)(t + 2) * kstep;
;     ...
;             PG8_WAIT_V(8); PG8_WAIT_L(0); PG8_BAR; PG8_MMA(0, 0, At, B0); PG8_MMA(0, 1, At, B1); PG8_BAR; PG8_SCHED;
;             PG8_LDA(At, 1, 1); PG8_STAGE(PG8_SB(1, 0), b3, voffB); PG8_STAGE(PG8_SB(1, 1), b3 + hstep, voffB); PG8_STAGE(PG8_SA(1, 0), a3, voffA);
;             PG8_WAIT_V(8); PG8_WAIT_L(0); PG8_BAR; PG8_MMA(1, 0, At, B0); PG8_MMA(1, 1, At, B1); PG8_BAR; PG8_SCHED;
	s_setprio 1
	s_waitcnt lgkmcnt(0)
	v_mfma_f32_16x16x32_bf16 v[126:129], v[130:133], v[184:187], v[126:129]
	v_mfma_f32_16x16x32_bf16 v[122:125], v[154:157], v[184:187], v[122:125]
	v_mfma_f32_16x16x32_bf16 v[118:121], v[130:133], v[192:195], v[118:121]
	v_mfma_f32_16x16x32_bf16 v[114:117], v[154:157], v[192:195], v[114:117]
	v_mfma_f32_16x16x32_bf16 v[110:113], v[130:133], v[204:207], v[110:113]
	v_mfma_f32_16x16x32_bf16 v[102:105], v[154:157], v[204:207], v[102:105]
	v_mfma_f32_16x16x32_bf16 v[82:85], v[130:133], v[212:215], v[82:85]
	v_mfma_f32_16x16x32_bf16 v[74:77], v[154:157], v[212:215], v[74:77]
	v_mfma_f32_16x16x32_bf16 v[126:129], v[134:137], v[188:191], v[126:129]
	v_mfma_f32_16x16x32_bf16 v[122:125], v[158:161], v[188:191], v[122:125]
	v_mfma_f32_16x16x32_bf16 v[118:121], v[134:137], v[200:203], v[118:121]
	v_mfma_f32_16x16x32_bf16 v[114:117], v[158:161], v[200:203], v[114:117]
	v_mfma_f32_16x16x32_bf16 v[110:113], v[134:137], v[208:211], v[110:113]
	v_mfma_f32_16x16x32_bf16 v[102:105], v[158:161], v[208:211], v[102:105]
	v_mfma_f32_16x16x32_bf16 v[82:85], v[134:137], v[216:219], v[82:85]
	v_mfma_f32_16x16x32_bf16 v[74:77], v[158:161], v[216:219], v[74:77]
	s_setprio 0
	s_setprio 1
	v_mfma_f32_16x16x32_bf16 v[106:109], v[168:171], v[184:187], v[106:109]
	v_mfma_f32_16x16x32_bf16 v[98:101], v[176:179], v[184:187], v[98:101]
	v_mfma_f32_16x16x32_bf16 v[94:97], v[168:171], v[192:195], v[94:97]
	v_mfma_f32_16x16x32_bf16 v[90:93], v[176:179], v[192:195], v[90:93]
	v_mfma_f32_16x16x32_bf16 v[86:89], v[168:171], v[204:207], v[86:89]
	v_mfma_f32_16x16x32_bf16 v[78:81], v[176:179], v[204:207], v[78:81]
	v_mfma_f32_16x16x32_bf16 v[70:73], v[168:171], v[212:215], v[70:73]
	v_mfma_f32_16x16x32_bf16 v[66:69], v[176:179], v[212:215], v[66:69]
	v_mfma_f32_16x16x32_bf16 v[106:109], v[172:175], v[188:191], v[106:109]
	v_mfma_f32_16x16x32_bf16 v[98:101], v[180:183], v[188:191], v[98:101]
	v_mfma_f32_16x16x32_bf16 v[94:97], v[172:175], v[200:203], v[94:97]
	v_mfma_f32_16x16x32_bf16 v[90:93], v[180:183], v[200:203], v[90:93]
	v_mfma_f32_16x16x32_bf16 v[86:89], v[172:175], v[208:211], v[86:89]
	v_mfma_f32_16x16x32_bf16 v[78:81], v[180:183], v[208:211], v[78:81]
	v_mfma_f32_16x16x32_bf16 v[70:73], v[172:175], v[216:219], v[70:73]
	v_mfma_f32_16x16x32_bf16 v[66:69], v[180:183], v[216:219], v[66:69]
	s_setprio 0
	s_barrier
	s_add_i32 s34, s52, s36
	v_lshl_add_u64 v[196:197], v[196:197], 0, s[6:7]
	s_mov_b32 m0, s34
	ds_read_b128 v[184:187], v166 offset:49152
	ds_read_b128 v[188:191], v166 offset:50176
	ds_read_b128 v[192:195], v166 offset:51200
	ds_read_b128 v[200:203], v166 offset:52224
	ds_read_b128 v[204:207], v166 offset:53248
	ds_read_b128 v[208:211], v166 offset:54272
	ds_read_b128 v[212:215], v166 offset:55296
	ds_read_b128 v[216:219], v166 offset:56320
	global_load_lds_dwordx4 v[196:197], off
	s_add_i32 m0, s34, 0x2000
	s_add_u32 s30, s30, 0x100080
	v_lshl_add_u64 v[196:197], v[220:221], 0, s[6:7]
	s_addc_u32 s31, s31, 0
	s_add_i32 s34, s53, s36
	global_load_lds_dwordx4 v[196:197], off
	v_lshl_add_u64 v[196:197], s[30:31], 0, v[140:141]
	s_mov_b32 m0, s34
	s_nop 0
	global_load_lds_dwordx4 v[196:197], off
	v_lshl_add_u64 v[196:197], s[30:31], 0, v[144:145]
	s_add_i32 m0, s34, 0x2000
	s_nop 0
	global_load_lds_dwordx4 v[196:197], off
	s_waitcnt vmcnt(6)
	s_waitcnt lgkmcnt(0)
	s_barrier
	s_setprio 1
	s_waitcnt lgkmcnt(0)
	v_mfma_f32_16x16x32_bf16 v[62:65], v[130:133], v[184:187], v[62:65]
	v_mfma_f32_16x16x32_bf16 v[58:61], v[154:157], v[184:187], v[58:61]
	v_mfma_f32_16x16x32_bf16 v[50:53], v[130:133], v[192:195], v[50:53]
	v_mfma_f32_16x16x32_bf16 v[42:45], v[154:157], v[192:195], v[42:45]
	v_mfma_f32_16x16x32_bf16 v[34:37], v[130:133], v[204:207], v[34:37]
	v_mfma_f32_16x16x32_bf16 v[26:29], v[154:157], v[204:207], v[26:29]
	v_mfma_f32_16x16x32_bf16 v[18:21], v[130:133], v[212:215], v[18:21]
	v_mfma_f32_16x16x32_bf16 v[10:13], v[154:157], v[212:215], v[10:13]
	v_mfma_f32_16x16x32_bf16 v[62:65], v[134:137], v[188:191], v[62:65]
	v_mfma_f32_16x16x32_bf16 v[58:61], v[158:161], v[188:191], v[58:61]
	v_mfma_f32_16x16x32_bf16 v[50:53], v[134:137], v[200:203], v[50:53]
	v_mfma_f32_16x16x32_bf16 v[42:45], v[158:161], v[200:203], v[42:45]
	v_mfma_f32_16x16x32_bf16 v[34:37], v[134:137], v[208:211], v[34:37]
	v_mfma_f32_16x16x32_bf16 v[26:29], v[158:161], v[208:211], v[26:29]
	v_mfma_f32_16x16x32_bf16 v[18:21], v[134:137], v[216:219], v[18:21]
	v_mfma_f32_16x16x32_bf16 v[10:13], v[158:161], v[216:219], v[10:13]
	s_setprio 0
	s_setprio 1
	v_mfma_f32_16x16x32_bf16 v[54:57], v[168:171], v[184:187], v[54:57]
	v_mfma_f32_16x16x32_bf16 v[46:49], v[176:179], v[184:187], v[46:49]
	v_mfma_f32_16x16x32_bf16 v[38:41], v[168:171], v[192:195], v[38:41]
	v_mfma_f32_16x16x32_bf16 v[30:33], v[176:179], v[192:195], v[30:33]
	v_mfma_f32_16x16x32_bf16 v[22:25], v[168:171], v[204:207], v[22:25]
	v_mfma_f32_16x16x32_bf16 v[14:17], v[176:179], v[204:207], v[14:17]
	v_mfma_f32_16x16x32_bf16 v[6:9], v[168:171], v[212:215], v[6:9]
	v_mfma_f32_16x16x32_bf16 v[2:5], v[176:179], v[212:215], v[2:5]
	v_mfma_f32_16x16x32_bf16 v[54:57], v[172:175], v[188:191], v[54:57]
	v_mfma_f32_16x16x32_bf16 v[46:49], v[180:183], v[188:191], v[46:49]
	v_mfma_f32_16x16x32_bf16 v[38:41], v[172:175], v[200:203], v[38:41]
	v_mfma_f32_16x16x32_bf16 v[30:33], v[180:183], v[200:203], v[30:33]
	v_mfma_f32_16x16x32_bf16 v[22:25], v[172:175], v[208:211], v[22:25]
	v_mfma_f32_16x16x32_bf16 v[14:17], v[180:183], v[208:211], v[14:17]
	v_mfma_f32_16x16x32_bf16 v[6:9], v[172:175], v[216:219], v[6:9]
	v_mfma_f32_16x16x32_bf16 v[2:5], v[180:183], v[216:219], v[2:5]
	s_setprio 0
	s_barrier
	s_add_i32 s51, s51, 2
	s_add_u32 s28, s28, 0x100
	s_addc_u32 s29, s29, 0
	s_add_u32 s49, s49, 0x100
	s_addc_u32 s50, s50, 0
	s_cmp_gt_u32 s51, 61
	s_cbranch_scc0 .LBB0_959
	s_and_b64 vcc, exec, s[8:9]
	s_cbranch_vccz .LBB0_962
	s_barrier

; #define PG8_STAGE(bufoff, gbase, voff) do { _Pragma("unroll") for (int _i = 0; _i < 2; ++_i) \
;         __builtin_amdgcn_global_load_lds((const unsigned*)((const char*)(gbase) + (voff)[_i]), (PG8_LAS unsigned*)(lds + (bufoff) + ldsw + _i * 8192), 16, 0, 0); } while (0)
; #define PG8_LDA(dst, b, h) do { _Pragma("unroll") for (int m = 0; m < 4; ++m) _Pragma("unroll") for (int k = 0; k < 2; ++k) dst[m][k] = *(const PG8_LAS bf16x8*)(lds + PG8_SA(b, h) + aoff + m * 2048 + k * 1024); } while (0)
; #define PG8_LDB(dst, b, h) do { _Pragma("unroll") for (int n = 0; n < 2; ++n) _Pragma("unroll") for (int k = 0; k < 2; ++k) dst[n][k] = *(const PG8_LAS bf16x8*)(lds + PG8_SB(b, h) + boff + n * 2048 + k * 1024); } while (0)
; #define PG8_MMA(ai, bj, At, Bt) do { __builtin_amdgcn_s_setprio(1); _Pragma("unroll") for (int m = 0; m < 4; ++m) _Pragma("unroll") for (int n = 0; n < 2; ++n) _Pragma("unroll") for (int k = 0; k < 2; ++k) \
;         acc[ai][bj][m][n] = __builtin_amdgcn_mfma_f32_16x16x32_bf16(Bt[n][k], At[m][k], acc[ai][bj][m][n], 0, 0, 0); __builtin_amdgcn_s_setprio(0); } while (0)
; #define PG8_WAIT_V(n) asm volatile("s_waitcnt vmcnt(" #n ")" ::: "memory")
; #define PG8_WAIT_L(n) asm volatile("s_waitcnt lgkmcnt(" #n ")" ::: "memory")
; #define PG8_BAR __builtin_amdgcn_s_barrier()
; #define PG8_SCHED __builtin_amdgcn_sched_barrier(0)
; template <class Epi, class Sched, bool ALIGN_EPI = false, bool SP2 = false>
; __device__ __forceinline__ void gemm_phase(PG8_LAS unsigned char* lds, const Gemm g, const Sched& S, const Epi& E) {
;     ...
;             PG8_LDB(B0, 0, 0); PG8_LDB(B1, 0, 1); PG8_SCHED; PG8_LDA(At, 0, 0); PG8_STAGE(PG8_SA(1, 1), a1 + hstep, voffA);
;             PG8_WAIT_V(8); PG8_WAIT_L(0); PG8_BAR; PG8_MMA(0, 0, At, B0); PG8_MMA(0, 1, At, B1); PG8_BAR; PG8_SCHED;
;             PG8_LDA(At, 0, 1); PG8_STAGE(PG8_SB(0, 0), b2, voffB); PG8_STAGE(PG8_SB(0, 1), b2 + hstep, voffB); PG8_STAGE(PG8_SA(0, 0), a2, voffA);
;             PG8_WAIT_V(8); PG8_WAIT_L(0); PG8_BAR; PG8_MMA(1, 0, At, B0); PG8_MMA(1, 1, At, B1); PG8_BAR; PG8_SCHED;
.LBB0_1081:
	s_add_u32 s34, s30, 0xfff00000
	s_addc_u32 s35, s31, -1
	v_lshl_add_u64 v[146:147], s[34:35], 0, v[136:137]
	s_mov_b32 m0, s44
	s_nop 0
	global_load_lds_dwordx4 v[146:147], off
	v_lshl_add_u64 v[146:147], s[34:35], 0, v[132:133]
	s_mov_b32 m0, s45
	s_nop 0
	global_load_lds_dwordx4 v[146:147], off
	s_add_u32 s34, s34, 0x80
	s_addc_u32 s35, s35, 0
	ds_read_b128 v[154:157], v150
	ds_read_b128 v[158:161], v150 offset:1024
	ds_read_b128 v[162:165], v150 offset:2048
	ds_read_b128 v[166:169], v150 offset:3072
	ds_read_b128 v[170:173], v151
	ds_read_b128 v[174:177], v151 offset:1024
	ds_read_b128 v[178:181], v151 offset:2048
	ds_read_b128 v[182:185], v151 offset:3072
	s_cmp_eq_u32 s55, 60
	s_cselect_b32 s37, s15, s35
	s_cselect_b32 s36, s51, s34
	s_cselect_b32 s35, s13, s54
	s_cselect_b32 s34, s52, s53
	v_lshl_add_u64 v[146:147], s[30:31], 0, v[138:139]
	s_add_i32 m0, s29, 0xc000
	ds_read_b128 v[186:189], v152
	ds_read_b128 v[190:193], v152 offset:1024
	ds_read_b128 v[194:197], v152 offset:2048
	ds_read_b128 v[200:203], v152 offset:3072
	ds_read_b128 v[204:207], v152 offset:4096
	ds_read_b128 v[208:211], v152 offset:5120
	ds_read_b128 v[212:215], v152 offset:6144
	ds_read_b128 v[216:219], v152 offset:7168
	global_load_lds_dwordx4 v[146:147], off
	v_lshl_add_u64 v[146:147], s[30:31], 0, v[140:141]
	s_add_i32 m0, s29, 0xe000
	s_nop 0
	global_load_lds_dwordx4 v[146:147], off
	s_waitcnt vmcnt(8)
	s_waitcnt lgkmcnt(0)
	s_barrier
	s_setprio 1
	s_waitcnt lgkmcnt(0)
	v_mfma_f32_16x16x32_bf16 v[126:129], v[154:157], v[186:189], v[126:129]
	v_mfma_f32_16x16x32_bf16 v[122:125], v[162:165], v[186:189], v[122:125]
	v_mfma_f32_16x16x32_bf16 v[110:113], v[154:157], v[194:197], v[110:113]
	v_mfma_f32_16x16x32_bf16 v[106:109], v[162:165], v[194:197], v[106:109]
	v_mfma_f32_16x16x32_bf16 v[94:97], v[154:157], v[204:207], v[94:97]
	v_mfma_f32_16x16x32_bf16 v[90:93], v[162:165], v[204:207], v[90:93]
	v_mfma_f32_16x16x32_bf16 v[78:81], v[154:157], v[212:215], v[78:81]
	v_mfma_f32_16x16x32_bf16 v[74:77], v[162:165], v[212:215], v[74:77]
	v_mfma_f32_16x16x32_bf16 v[126:129], v[158:161], v[190:193], v[126:129]
	v_mfma_f32_16x16x32_bf16 v[122:125], v[166:169], v[190:193], v[122:125]
	v_mfma_f32_16x16x32_bf16 v[110:113], v[158:161], v[200:203], v[110:113]
	v_mfma_f32_16x16x32_bf16 v[106:109], v[166:169], v[200:203], v[106:109]
	v_mfma_f32_16x16x32_bf16 v[94:97], v[158:161], v[208:211], v[94:97]
	v_mfma_f32_16x16x32_bf16 v[90:93], v[166:169], v[208:211], v[90:93]
	v_mfma_f32_16x16x32_bf16 v[78:81], v[158:161], v[216:219], v[78:81]
	v_mfma_f32_16x16x32_bf16 v[74:77], v[166:169], v[216:219], v[74:77]
	s_setprio 0
	s_setprio 1
	v_mfma_f32_16x16x32_bf16 v[118:121], v[170:173], v[186:189], v[118:121]
	v_mfma_f32_16x16x32_bf16 v[114:117], v[178:181], v[186:189], v[114:117]
	v_mfma_f32_16x16x32_bf16 v[102:105], v[170:173], v[194:197], v[102:105]
	v_mfma_f32_16x16x32_bf16 v[98:101], v[178:181], v[194:197], v[98:101]
	v_mfma_f32_16x16x32_bf16 v[86:89], v[170:173], v[204:207], v[86:89]
	v_mfma_f32_16x16x32_bf16 v[82:85], v[178:181], v[204:207], v[82:85]
	v_mfma_f32_16x16x32_bf16 v[70:73], v[170:173], v[212:215], v[70:73]
	v_mfma_f32_16x16x32_bf16 v[66:69], v[178:181], v[212:215], v[66:69]
	v_mfma_f32_16x16x32_bf16 v[118:121], v[174:177], v[190:193], v[118:121]
	v_mfma_f32_16x16x32_bf16 v[114:117], v[182:185], v[190:193], v[114:117]
	v_mfma_f32_16x16x32_bf16 v[102:105], v[174:177], v[200:203], v[102:105]
	v_mfma_f32_16x16x32_bf16 v[98:101], v[182:185], v[200:203], v[98:101]
	v_mfma_f32_16x16x32_bf16 v[86:89], v[174:177], v[208:211], v[86:89]
	v_mfma_f32_16x16x32_bf16 v[82:85], v[182:185], v[208:211], v[82:85]
	v_mfma_f32_16x16x32_bf16 v[70:73], v[174:177], v[216:219], v[70:73]
	v_mfma_f32_16x16x32_bf16 v[66:69], v[182:185], v[216:219], v[66:69]
	s_setprio 0
	s_barrier
	s_add_i32 s56, s47, s33
	v_lshl_add_u64 v[146:147], s[34:35], 0, v[134:135]
	s_mov_b32 m0, s56
	ds_read_b128 v[186:189], v152 offset:16384
	ds_read_b128 v[190:193], v152 offset:17408
	ds_read_b128 v[194:197], v152 offset:18432
	ds_read_b128 v[200:203], v152 offset:19456
	ds_read_b128 v[204:207], v152 offset:20480
	ds_read_b128 v[208:211], v152 offset:21504
	ds_read_b128 v[212:215], v152 offset:22528
	ds_read_b128 v[216:219], v152 offset:23552
	global_load_lds_dwordx4 v[146:147], off
	s_add_i32 m0, s56, 0x2000
	s_add_u32 s56, s34, 0x100000
	v_lshl_add_u64 v[220:221], s[34:35], 0, v[130:131]
	s_addc_u32 s57, s35, 0
	s_add_i32 s58, s48, s33
	global_load_lds_dwordx4 v[220:221], off
	v_lshl_add_u64 v[222:223], s[56:57], 0, v[134:135]
	s_mov_b32 m0, s58
	v_lshl_add_u64 v[224:225], s[36:37], 0, v[132:133]
	global_load_lds_dwordx4 v[222:223], off
	v_lshl_add_u64 v[222:223], s[56:57], 0, v[130:131]
	s_add_i32 m0, s58, 0x2000
	s_nop 0
	global_load_lds_dwordx4 v[222:223], off
	v_lshl_add_u64 v[222:223], s[36:37], 0, v[136:137]
	s_waitcnt vmcnt(6)
	s_waitcnt lgkmcnt(0)
	s_barrier
; #define PG8_STAGE(bufoff, gbase, voff) do { _Pragma("unroll") for (int _i = 0; _i < 2; ++_i) \
;         __builtin_amdgcn_global_load_lds((const unsigned*)((const char*)(gbase) + (voff)[_i]), (PG8_LAS unsigned*)(lds + (bufoff) + ldsw + _i * 8192), 16, 0, 0); } while (0)
; #define PG8_LDA(dst, b, h) do { _Pragma("unroll") for (int m = 0; m < 4; ++m) _Pragma("unroll") for (int k = 0; k < 2; ++k) dst[m][k] = *(const PG8_LAS bf16x8*)(lds + PG8_SA(b, h) + aoff + m * 2048 + k * 1024); } while (0)
; #define PG8_LDB(dst, b, h) do { _Pragma("unroll") for (int n = 0; n < 2; ++n) _Pragma("unroll") for (int k = 0; k < 2; ++k) dst[n][k] = *(const PG8_LAS bf16x8*)(lds + PG8_SB(b, h) + boff + n * 2048 + k * 1024); } while (0)
; #define PG8_MMA(ai, bj, At, Bt) do { __builtin_amdgcn_s_setprio(1); _Pragma("unroll") for (int m = 0; m < 4; ++m) _Pragma("unroll") for (int n = 0; n < 2; ++n) _Pragma("unroll") for (int k = 0; k < 2; ++k) \
;         acc[ai][bj][m][n] = __builtin_amdgcn_mfma_f32_16x16x32_bf16(Bt[n][k], At[m][k], acc[ai][bj][m][n], 0, 0, 0); __builtin_amdgcn_s_setprio(0); } while (0)
; #define PG8_WAIT_V(n) asm volatile("s_waitcnt vmcnt(" #n ")" ::: "memory")
; #define PG8_WAIT_L(n) asm volatile("s_waitcnt lgkmcnt(" #n ")" ::: "memory")
; #define PG8_BAR __builtin_amdgcn_s_barrier()
; #define PG8_SCHED __builtin_amdgcn_sched_barrier(0)
; template <class Epi, class Sched, bool ALIGN_EPI = false, bool SP2 = false>
; __device__ __forceinline__ void gemm_phase(PG8_LAS unsigned char* lds, const Gemm g, const Sched& S, const Epi& E) {
;     ...
;             PG8_WAIT_V(8); PG8_WAIT_L(0); PG8_BAR; PG8_MMA(1, 0, At, B0); PG8_MMA(1, 1, At, B1); PG8_BAR; PG8_SCHED;
;             PG8_LDB(B0, 1, 0); PG8_LDB(B1, 1, 1); PG8_SCHED; PG8_LDA(At, 1, 0); PG8_STAGE(PG8_SA(0, 1), a2 + hstep, voffA);
	s_setprio 1
	s_waitcnt lgkmcnt(0)
	v_mfma_f32_16x16x32_bf16 v[62:65], v[154:157], v[186:189], v[62:65]
	v_mfma_f32_16x16x32_bf16 v[58:61], v[162:165], v[186:189], v[58:61]
	v_mfma_f32_16x16x32_bf16 v[46:49], v[154:157], v[194:197], v[46:49]
	v_mfma_f32_16x16x32_bf16 v[42:45], v[162:165], v[194:197], v[42:45]
	v_mfma_f32_16x16x32_bf16 v[30:33], v[154:157], v[204:207], v[30:33]
	v_mfma_f32_16x16x32_bf16 v[26:29], v[162:165], v[204:207], v[26:29]
	v_mfma_f32_16x16x32_bf16 v[14:17], v[154:157], v[212:215], v[14:17]
	v_mfma_f32_16x16x32_bf16 v[10:13], v[162:165], v[212:215], v[10:13]
	v_mfma_f32_16x16x32_bf16 v[62:65], v[158:161], v[190:193], v[62:65]
	v_mfma_f32_16x16x32_bf16 v[58:61], v[166:169], v[190:193], v[58:61]
	v_mfma_f32_16x16x32_bf16 v[46:49], v[158:161], v[200:203], v[46:49]
	v_mfma_f32_16x16x32_bf16 v[42:45], v[166:169], v[200:203], v[42:45]
	v_mfma_f32_16x16x32_bf16 v[30:33], v[158:161], v[208:211], v[30:33]
	v_mfma_f32_16x16x32_bf16 v[26:29], v[166:169], v[208:211], v[26:29]
	v_mfma_f32_16x16x32_bf16 v[14:17], v[158:161], v[216:219], v[14:17]
	v_mfma_f32_16x16x32_bf16 v[10:13], v[166:169], v[216:219], v[10:13]
	s_setprio 0
	s_setprio 1
	v_mfma_f32_16x16x32_bf16 v[54:57], v[170:173], v[186:189], v[54:57]
	v_mfma_f32_16x16x32_bf16 v[50:53], v[178:181], v[186:189], v[50:53]
	v_mfma_f32_16x16x32_bf16 v[38:41], v[170:173], v[194:197], v[38:41]
	v_mfma_f32_16x16x32_bf16 v[34:37], v[178:181], v[194:197], v[34:37]
	v_mfma_f32_16x16x32_bf16 v[22:25], v[170:173], v[204:207], v[22:25]
	v_mfma_f32_16x16x32_bf16 v[18:21], v[178:181], v[204:207], v[18:21]
	v_mfma_f32_16x16x32_bf16 v[6:9], v[170:173], v[212:215], v[6:9]
	v_mfma_f32_16x16x32_bf16 v[2:5], v[178:181], v[212:215], v[2:5]
	v_mfma_f32_16x16x32_bf16 v[54:57], v[174:177], v[190:193], v[54:57]
	v_mfma_f32_16x16x32_bf16 v[50:53], v[182:185], v[190:193], v[50:53]
	v_mfma_f32_16x16x32_bf16 v[38:41], v[174:177], v[200:203], v[38:41]
	v_mfma_f32_16x16x32_bf16 v[34:37], v[182:185], v[200:203], v[34:37]
	v_mfma_f32_16x16x32_bf16 v[22:25], v[174:177], v[208:211], v[22:25]
	v_mfma_f32_16x16x32_bf16 v[18:21], v[182:185], v[208:211], v[18:21]
	v_mfma_f32_16x16x32_bf16 v[6:9], v[174:177], v[216:219], v[6:9]
	v_mfma_f32_16x16x32_bf16 v[2:5], v[182:185], v[216:219], v[2:5]
	s_setprio 0
	s_barrier
	s_mov_b32 m0, s29
	s_nop 0
	global_load_lds_dwordx4 v[222:223], off
	s_mov_b32 m0, s40
	s_nop 0
	global_load_lds_dwordx4 v[224:225], off
	s_add_i32 s56, 0, 0x18000
	v_add_u32_e32 v153, s56, v148
	s_add_i32 s57, 0, 0x1c000
	ds_read_b128 v[154:157], v153
	ds_read_b128 v[158:161], v153 offset:1024
	ds_read_b128 v[162:165], v153 offset:2048
	ds_read_b128 v[166:169], v153 offset:3072
	v_add_u32_e32 v153, s57, v148
	ds_read_b128 v[170:173], v153
	ds_read_b128 v[174:177], v153 offset:1024
	ds_read_b128 v[178:181], v153 offset:2048
	ds_read_b128 v[182:185], v153 offset:3072
	s_add_u32 s36, s36, 0x100000
	s_addc_u32 s37, s37, 0
	s_mov_b32 m0, s41
	v_lshl_add_u64 v[226:227], s[36:37], 0, v[136:137]
	ds_read_b128 v[186:189], v152 offset:32768
	ds_read_b128 v[190:193], v152 offset:33792
	ds_read_b128 v[194:197], v152 offset:34816
	ds_read_b128 v[200:203], v152 offset:35840
	ds_read_b128 v[204:207], v152 offset:36864
	ds_read_b128 v[208:211], v152 offset:37888
	ds_read_b128 v[212:215], v152 offset:38912
	ds_read_b128 v[216:219], v152 offset:39936
	global_load_lds_dwordx4 v[226:227], off
	v_lshl_add_u64 v[226:227], s[36:37], 0, v[132:133]
	s_mov_b32 m0, s42
	s_nop 0
	global_load_lds_dwordx4 v[226:227], off
	s_waitcnt vmcnt(8)
	s_waitcnt lgkmcnt(0)
	s_barrier
; #define PG8_STAGE(bufoff, gbase, voff) do { _Pragma("unroll") for (int _i = 0; _i < 2; ++_i) \
;         __builtin_amdgcn_global_load_lds((const unsigned*)((const char*)(gbase) + (voff)[_i]), (PG8_LAS unsigned*)(lds + (bufoff) + ldsw + _i * 8192), 16, 0, 0); } while (0)
; #define PG8_LDA(dst, b, h) do { _Pragma("unroll") for (int m = 0; m < 4; ++m) _Pragma("unroll") for (int k = 0; k < 2; ++k) dst[m][k] = *(const PG8_LAS bf16x8*)(lds + PG8_SA(b, h) + aoff + m * 2048 + k * 1024); } while (0)
; #define PG8_MMA(ai, bj, At, Bt) do { __builtin_amdgcn_s_setprio(1); _Pragma("unroll") for (int m = 0; m < 4; ++m) _Pragma("unroll") for (int n = 0; n < 2; ++n) _Pragma("unroll") for (int k = 0; k < 2; ++k) \
;         acc[ai][bj][m][n] = __builtin_amdgcn_mfma_f32_16x16x32_bf16(Bt[n][k], At[m][k], acc[ai][bj][m][n], 0, 0, 0); __builtin_amdgcn_s_setprio(0); } while (0)
; #define PG8_WAIT_V(n) asm volatile("s_waitcnt vmcnt(" #n ")" ::: "memory")
; #define PG8_WAIT_L(n) asm volatile("s_waitcnt lgkmcnt(" #n ")" ::: "memory")
; #define PG8_BAR __builtin_amdgcn_s_barrier()
; #define PG8_SCHED __builtin_amdgcn_sched_barrier(0)
; template <class Epi, class Sched, bool ALIGN_EPI = false, bool SP2 = false>
; __device__ __forceinline__ void gemm_phase(PG8_LAS unsigned char* lds, const Gemm g, const Sched& S, const Epi& E) {
;     ...
;         for (int t = 0; t < nt; t += 2) {
;             const bool last = (t == nt - 2);
;             const char* a1 = cA + (size_t)(t + 1) * kstep;
;             const char* a2 = last ? nA : cA + (size_t)(t + 2) * kstep; const char* b2 = last ? nB : cB + (size_t)(t + 2) * kstep;
;     ...
;             PG8_WAIT_V(8); PG8_WAIT_L(0); PG8_BAR; PG8_MMA(0, 0, At, B0); PG8_MMA(0, 1, At, B1); PG8_BAR; PG8_SCHED;
;             PG8_LDA(At, 1, 1); PG8_STAGE(PG8_SB(1, 0), b3, voffB); PG8_STAGE(PG8_SB(1, 1), b3 + hstep, voffB); PG8_STAGE(PG8_SA(1, 0), a3, voffA);
;             PG8_WAIT_V(8); PG8_WAIT_L(0); PG8_BAR; PG8_MMA(1, 0, At, B0); PG8_MMA(1, 1, At, B1); PG8_BAR; PG8_SCHED;
	s_setprio 1
	s_waitcnt lgkmcnt(0)
	v_mfma_f32_16x16x32_bf16 v[126:129], v[154:157], v[186:189], v[126:129]
	v_mfma_f32_16x16x32_bf16 v[122:125], v[162:165], v[186:189], v[122:125]
	v_mfma_f32_16x16x32_bf16 v[110:113], v[154:157], v[194:197], v[110:113]
	v_mfma_f32_16x16x32_bf16 v[106:109], v[162:165], v[194:197], v[106:109]
	v_mfma_f32_16x16x32_bf16 v[94:97], v[154:157], v[204:207], v[94:97]
	v_mfma_f32_16x16x32_bf16 v[90:93], v[162:165], v[204:207], v[90:93]
	v_mfma_f32_16x16x32_bf16 v[78:81], v[154:157], v[212:215], v[78:81]
	v_mfma_f32_16x16x32_bf16 v[74:77], v[162:165], v[212:215], v[74:77]
	v_mfma_f32_16x16x32_bf16 v[126:129], v[158:161], v[190:193], v[126:129]
	v_mfma_f32_16x16x32_bf16 v[122:125], v[166:169], v[190:193], v[122:125]
	v_mfma_f32_16x16x32_bf16 v[110:113], v[158:161], v[200:203], v[110:113]
	v_mfma_f32_16x16x32_bf16 v[106:109], v[166:169], v[200:203], v[106:109]
	v_mfma_f32_16x16x32_bf16 v[94:97], v[158:161], v[208:211], v[94:97]
	v_mfma_f32_16x16x32_bf16 v[90:93], v[166:169], v[208:211], v[90:93]
	v_mfma_f32_16x16x32_bf16 v[78:81], v[158:161], v[216:219], v[78:81]
	v_mfma_f32_16x16x32_bf16 v[74:77], v[166:169], v[216:219], v[74:77]
	s_setprio 0
	s_setprio 1
	v_mfma_f32_16x16x32_bf16 v[118:121], v[170:173], v[186:189], v[118:121]
	v_mfma_f32_16x16x32_bf16 v[114:117], v[178:181], v[186:189], v[114:117]
	v_mfma_f32_16x16x32_bf16 v[102:105], v[170:173], v[194:197], v[102:105]
	v_mfma_f32_16x16x32_bf16 v[98:101], v[178:181], v[194:197], v[98:101]
	v_mfma_f32_16x16x32_bf16 v[86:89], v[170:173], v[204:207], v[86:89]
	v_mfma_f32_16x16x32_bf16 v[82:85], v[178:181], v[204:207], v[82:85]
	v_mfma_f32_16x16x32_bf16 v[70:73], v[170:173], v[212:215], v[70:73]
	v_mfma_f32_16x16x32_bf16 v[66:69], v[178:181], v[212:215], v[66:69]
	v_mfma_f32_16x16x32_bf16 v[118:121], v[174:177], v[190:193], v[118:121]
	v_mfma_f32_16x16x32_bf16 v[114:117], v[182:185], v[190:193], v[114:117]
	v_mfma_f32_16x16x32_bf16 v[102:105], v[174:177], v[200:203], v[102:105]
	v_mfma_f32_16x16x32_bf16 v[98:101], v[182:185], v[200:203], v[98:101]
	v_mfma_f32_16x16x32_bf16 v[86:89], v[174:177], v[208:211], v[86:89]
	v_mfma_f32_16x16x32_bf16 v[82:85], v[182:185], v[208:211], v[82:85]
	v_mfma_f32_16x16x32_bf16 v[70:73], v[174:177], v[216:219], v[70:73]
	v_mfma_f32_16x16x32_bf16 v[66:69], v[182:185], v[216:219], v[66:69]
	s_setprio 0
	s_barrier
	s_add_i32 s36, s56, s33
	v_lshl_add_u64 v[146:147], v[146:147], 0, s[8:9]
	s_mov_b32 m0, s36
	ds_read_b128 v[186:189], v152 offset:49152
	ds_read_b128 v[190:193], v152 offset:50176
	ds_read_b128 v[194:197], v152 offset:51200
	ds_read_b128 v[200:203], v152 offset:52224
	ds_read_b128 v[204:207], v152 offset:53248
	ds_read_b128 v[208:211], v152 offset:54272
	ds_read_b128 v[212:215], v152 offset:55296
	ds_read_b128 v[216:219], v152 offset:56320
	global_load_lds_dwordx4 v[146:147], off
	s_add_i32 m0, s36, 0x2000
	s_add_u32 s34, s34, 0x100080
	v_lshl_add_u64 v[146:147], v[220:221], 0, s[8:9]
	s_addc_u32 s35, s35, 0
	s_add_i32 s36, s57, s33
	global_load_lds_dwordx4 v[146:147], off
	v_lshl_add_u64 v[146:147], s[34:35], 0, v[134:135]
	s_mov_b32 m0, s36
	s_nop 0
	global_load_lds_dwordx4 v[146:147], off
	v_lshl_add_u64 v[146:147], s[34:35], 0, v[130:131]
	s_add_i32 m0, s36, 0x2000
	s_nop 0
	global_load_lds_dwordx4 v[146:147], off
	s_waitcnt vmcnt(6)
	s_waitcnt lgkmcnt(0)
	s_barrier
	s_setprio 1
	s_waitcnt lgkmcnt(0)
	v_mfma_f32_16x16x32_bf16 v[62:65], v[154:157], v[186:189], v[62:65]
	v_mfma_f32_16x16x32_bf16 v[58:61], v[162:165], v[186:189], v[58:61]
	v_mfma_f32_16x16x32_bf16 v[46:49], v[154:157], v[194:197], v[46:49]
	v_mfma_f32_16x16x32_bf16 v[42:45], v[162:165], v[194:197], v[42:45]
	v_mfma_f32_16x16x32_bf16 v[30:33], v[154:157], v[204:207], v[30:33]
	v_mfma_f32_16x16x32_bf16 v[26:29], v[162:165], v[204:207], v[26:29]
	v_mfma_f32_16x16x32_bf16 v[14:17], v[154:157], v[212:215], v[14:17]
	v_mfma_f32_16x16x32_bf16 v[10:13], v[162:165], v[212:215], v[10:13]
	v_mfma_f32_16x16x32_bf16 v[62:65], v[158:161], v[190:193], v[62:65]
	v_mfma_f32_16x16x32_bf16 v[58:61], v[166:169], v[190:193], v[58:61]
	v_mfma_f32_16x16x32_bf16 v[46:49], v[158:161], v[200:203], v[46:49]
	v_mfma_f32_16x16x32_bf16 v[42:45], v[166:169], v[200:203], v[42:45]
	v_mfma_f32_16x16x32_bf16 v[30:33], v[158:161], v[208:211], v[30:33]
	v_mfma_f32_16x16x32_bf16 v[26:29], v[166:169], v[208:211], v[26:29]
	v_mfma_f32_16x16x32_bf16 v[14:17], v[158:161], v[216:219], v[14:17]
	v_mfma_f32_16x16x32_bf16 v[10:13], v[166:169], v[216:219], v[10:13]
	s_setprio 0
	s_setprio 1
	v_mfma_f32_16x16x32_bf16 v[54:57], v[170:173], v[186:189], v[54:57]
	v_mfma_f32_16x16x32_bf16 v[50:53], v[178:181], v[186:189], v[50:53]
	v_mfma_f32_16x16x32_bf16 v[38:41], v[170:173], v[194:197], v[38:41]
	v_mfma_f32_16x16x32_bf16 v[34:37], v[178:181], v[194:197], v[34:37]
	v_mfma_f32_16x16x32_bf16 v[22:25], v[170:173], v[204:207], v[22:25]
	v_mfma_f32_16x16x32_bf16 v[18:21], v[178:181], v[204:207], v[18:21]
	v_mfma_f32_16x16x32_bf16 v[6:9], v[170:173], v[212:215], v[6:9]
	v_mfma_f32_16x16x32_bf16 v[2:5], v[178:181], v[212:215], v[2:5]
	v_mfma_f32_16x16x32_bf16 v[54:57], v[174:177], v[190:193], v[54:57]
	v_mfma_f32_16x16x32_bf16 v[50:53], v[182:185], v[190:193], v[50:53]
	v_mfma_f32_16x16x32_bf16 v[38:41], v[174:177], v[200:203], v[38:41]
	v_mfma_f32_16x16x32_bf16 v[34:37], v[182:185], v[200:203], v[34:37]
	v_mfma_f32_16x16x32_bf16 v[22:25], v[174:177], v[208:211], v[22:25]
	v_mfma_f32_16x16x32_bf16 v[18:21], v[182:185], v[208:211], v[18:21]
	v_mfma_f32_16x16x32_bf16 v[6:9], v[174:177], v[216:219], v[6:9]
	v_mfma_f32_16x16x32_bf16 v[2:5], v[182:185], v[216:219], v[2:5]
	s_setprio 0
	s_barrier
	s_add_i32 s55, s55, 2
	s_add_u32 s30, s30, 0x100
	s_addc_u32 s31, s31, 0
	s_add_u32 s53, s53, 0x100
	s_addc_u32 s54, s54, 0
	s_cmp_gt_u32 s55, 61
	s_cbranch_scc0 .LBB0_1081
	s_and_b64 vcc, exec, s[10:11]
	s_cbranch_vccz .LBB0_1084
	s_barrier
